# plus non-temporal hint on P1/P4 projection epilogue stores
# speedup vs baseline: 1.0112x; 1.0068x over previous
.LBB0_325:
	s_andn2_b64 vcc, exec, s[4:5]
	s_mov_b64 s[4:5], -1
	global_store_dwordx4 v[174:175], v[112:115], off offset:256 nt
	s_cbranch_vccnz .LBB0_310
	s_branch .LBB0_440

.LBB0_328:
	s_cmp_eq_u32 s9, 2
	v_readlane_b32 s72, v254, 16
	s_cselect_b32 s6, s60, 0x16000000
	v_readlane_b32 s78, v254, 22
	v_readlane_b32 s79, v254, 23
	s_add_u32 s6, s78, s6
	s_addc_u32 s7, s79, 0
	s_lshl_b32 s9, s27, 1
	s_add_u32 s6, s6, s9
	s_addc_u32 s7, s7, 0
	s_lshl_b32 s9, s52, 1
	s_add_u32 s6, s6, s9
	s_addc_u32 s7, s7, 0
	s_lshl_b32 s9, s34, 8
	v_add_u32_e32 v126, s9, v163
	v_lshlrev_b32_e32 v160, 1, v162
	v_ashrrev_i32_e32 v127, 31, v126
	v_lshl_add_u64 v[124:125], s[6:7], 0, v[160:161]
	v_lshlrev_b64 v[126:127], 12, v[126:127]
	v_lshl_add_u64 v[126:127], v[124:125], 0, v[126:127]
	v_cvt_pk_bf16_f32 v112, v112, v113
	v_cvt_pk_bf16_f32 v113, v114, v115
	v_cvt_pk_bf16_f32 v114, v116, v117
	v_cvt_pk_bf16_f32 v115, v118, v119
	global_store_dwordx4 v[126:127], v[112:115], off nt
	v_mov_b64_e32 v[116:117], v[128:129]
	s_andn2_b64 vcc, exec, s[36:37]
	v_cndmask_b32_e64 v112, 0, 1, s[36:37]
	v_cmp_ne_u32_e64 s[6:7], 1, v112
	v_mov_b64_e32 v[112:113], v[120:121]
	v_mov_b64_e32 v[114:115], v[122:123]
	v_mov_b64_e32 v[118:119], v[130:131]
	v_readlane_b32 s73, v254, 17
	v_readlane_b32 s74, v254, 18
	v_readlane_b32 s75, v254, 19
	v_readlane_b32 s76, v254, 20
	v_readlane_b32 s77, v254, 21
	s_cbranch_vccnz .LBB0_330
	v_mul_f32_e32 v113, 0xbfb8aa3b, v128
	v_mul_f32_e32 v114, 0xbfb8aa3b, v121
	v_exp_f32_e32 v113, v113
	v_exp_f32_e32 v114, v114
	v_mul_f32_e32 v115, 0xbfb8aa3b, v122
	v_mul_f32_e32 v117, 0xbfb8aa3b, v130
	v_add_f32_e32 v113, 1.0, v113
	v_rcp_f32_e32 v116, v113
	v_add_f32_e32 v113, 1.0, v114
	v_mul_f32_e32 v114, 0xbfb8aa3b, v129
	v_exp_f32_e32 v114, v114
	v_exp_f32_e32 v115, v115
	v_exp_f32_e32 v117, v117
	v_mul_f32_e32 v112, 0xbfb8aa3b, v120
	v_add_f32_e32 v132, 1.0, v114
	v_add_f32_e32 v114, 1.0, v115
	v_add_f32_e32 v115, 1.0, v117
	v_mul_f32_e32 v117, 0xbfb8aa3b, v123
	v_mul_f32_e32 v118, 0xbfb8aa3b, v131
	v_exp_f32_e32 v112, v112
	v_exp_f32_e32 v117, v117
	v_exp_f32_e32 v119, v118
	v_rcp_f32_e32 v118, v115
	v_add_f32_e32 v112, 1.0, v112
	v_add_f32_e32 v115, 1.0, v117
	v_add_f32_e32 v117, 1.0, v119
	v_rcp_f32_e32 v112, v112
	v_rcp_f32_e32 v113, v113
	v_rcp_f32_e32 v114, v114
	v_rcp_f32_e32 v115, v115
	v_rcp_f32_e32 v119, v117
	v_rcp_f32_e32 v117, v132
	v_pk_mul_f32 v[112:113], v[120:121], v[112:113]
	v_pk_mul_f32 v[114:115], v[122:123], v[114:115]
	v_pk_mul_f32 v[118:119], v[130:131], v[118:119]
	v_pk_mul_f32 v[116:117], v[128:129], v[116:117]
.LBB0_330:
	v_cvt_pk_bf16_f32 v112, v112, v113
	v_cvt_pk_bf16_f32 v113, v114, v115
	s_nop 0
	v_cvt_pk_bf16_f32 v114, v116, v117
	v_cvt_pk_bf16_f32 v115, v118, v119
	global_store_dwordx4 v[126:127], v[112:115], off offset:256 nt
	v_mov_b64_e32 v[118:119], v[110:111]
	s_and_b64 vcc, exec, s[6:7]
	v_mov_b64_e32 v[114:115], v[106:107]
	v_mov_b64_e32 v[112:113], v[104:105]
	v_mov_b64_e32 v[116:117], v[108:109]
	s_cbranch_vccnz .LBB0_332
	v_mul_f32_e32 v113, 0xbfb8aa3b, v108
	v_mul_f32_e32 v114, 0xbfb8aa3b, v105
	v_exp_f32_e32 v113, v113
	v_exp_f32_e32 v114, v114
	v_mul_f32_e32 v115, 0xbfb8aa3b, v106
	v_mul_f32_e32 v117, 0xbfb8aa3b, v110
	v_add_f32_e32 v113, 1.0, v113
	v_rcp_f32_e32 v116, v113
	v_add_f32_e32 v113, 1.0, v114
	v_mul_f32_e32 v114, 0xbfb8aa3b, v109
	v_exp_f32_e32 v114, v114
	v_exp_f32_e32 v115, v115
	v_exp_f32_e32 v117, v117
	v_mul_f32_e32 v112, 0xbfb8aa3b, v104
	v_add_f32_e32 v126, 1.0, v114
	v_add_f32_e32 v114, 1.0, v115
	v_add_f32_e32 v115, 1.0, v117
	v_mul_f32_e32 v117, 0xbfb8aa3b, v107
	v_mul_f32_e32 v118, 0xbfb8aa3b, v111
	v_exp_f32_e32 v112, v112
	v_exp_f32_e32 v117, v117
	v_exp_f32_e32 v119, v118
	v_rcp_f32_e32 v118, v115
	v_add_f32_e32 v112, 1.0, v112
	v_add_f32_e32 v115, 1.0, v117
	v_add_f32_e32 v117, 1.0, v119
	v_rcp_f32_e32 v112, v112
	v_rcp_f32_e32 v113, v113
	v_rcp_f32_e32 v114, v114
	v_rcp_f32_e32 v115, v115
	v_rcp_f32_e32 v119, v117
	v_rcp_f32_e32 v117, v126
	v_pk_mul_f32 v[112:113], v[104:105], v[112:113]
	v_pk_mul_f32 v[114:115], v[106:107], v[114:115]
	v_pk_mul_f32 v[118:119], v[110:111], v[118:119]
	v_pk_mul_f32 v[116:117], v[108:109], v[116:117]
.LBB0_332:
	v_or_b32_e32 v126, 16, v163
	v_add_u32_e32 v126, s9, v126
	v_ashrrev_i32_e32 v127, 31, v126
	v_lshlrev_b64 v[126:127], 12, v[126:127]
	v_lshl_add_u64 v[126:127], v[124:125], 0, v[126:127]
	v_cvt_pk_bf16_f32 v112, v112, v113
	v_cvt_pk_bf16_f32 v113, v114, v115
	v_cvt_pk_bf16_f32 v114, v116, v117
	v_cvt_pk_bf16_f32 v115, v118, v119
	global_store_dwordx4 v[126:127], v[112:115], off nt
	v_mov_b64_e32 v[118:119], v[102:103]
	s_and_b64 vcc, exec, s[6:7]
	v_mov_b64_e32 v[114:115], v[98:99]
	v_mov_b64_e32 v[112:113], v[96:97]
	v_mov_b64_e32 v[116:117], v[100:101]
	s_cbranch_vccnz .LBB0_334
	v_mul_f32_e32 v113, 0xbfb8aa3b, v100
	v_mul_f32_e32 v114, 0xbfb8aa3b, v97
	v_exp_f32_e32 v113, v113
	v_exp_f32_e32 v114, v114
	v_mul_f32_e32 v115, 0xbfb8aa3b, v98
	v_mul_f32_e32 v117, 0xbfb8aa3b, v102
	v_add_f32_e32 v113, 1.0, v113
	v_rcp_f32_e32 v116, v113
	v_add_f32_e32 v113, 1.0, v114
	v_mul_f32_e32 v114, 0xbfb8aa3b, v101
	v_exp_f32_e32 v114, v114
	v_exp_f32_e32 v115, v115
	v_exp_f32_e32 v117, v117
	v_mul_f32_e32 v112, 0xbfb8aa3b, v96
	v_add_f32_e32 v132, 1.0, v114
	v_add_f32_e32 v114, 1.0, v115
	v_add_f32_e32 v115, 1.0, v117
	v_mul_f32_e32 v117, 0xbfb8aa3b, v99
	v_mul_f32_e32 v118, 0xbfb8aa3b, v103
	v_exp_f32_e32 v112, v112
	v_exp_f32_e32 v117, v117
	v_exp_f32_e32 v119, v118
	v_rcp_f32_e32 v118, v115
	v_add_f32_e32 v112, 1.0, v112
	v_add_f32_e32 v115, 1.0, v117
	v_add_f32_e32 v117, 1.0, v119
	v_rcp_f32_e32 v112, v112
	v_rcp_f32_e32 v113, v113
	v_rcp_f32_e32 v114, v114
	v_rcp_f32_e32 v115, v115
	v_rcp_f32_e32 v119, v117
	v_rcp_f32_e32 v117, v132
	v_pk_mul_f32 v[112:113], v[96:97], v[112:113]
	v_pk_mul_f32 v[114:115], v[98:99], v[114:115]
	v_pk_mul_f32 v[118:119], v[102:103], v[118:119]
	v_pk_mul_f32 v[116:117], v[100:101], v[116:117]
.LBB0_334:
	v_cvt_pk_bf16_f32 v112, v112, v113
	v_cvt_pk_bf16_f32 v113, v114, v115
	s_nop 0
	v_cvt_pk_bf16_f32 v114, v116, v117
	v_cvt_pk_bf16_f32 v115, v118, v119
	global_store_dwordx4 v[126:127], v[112:115], off offset:256 nt
	v_mov_b64_e32 v[118:119], v[94:95]
	s_and_b64 vcc, exec, s[6:7]
	v_mov_b64_e32 v[114:115], v[90:91]
	v_mov_b64_e32 v[112:113], v[88:89]
	v_mov_b64_e32 v[116:117], v[92:93]
	s_cbranch_vccnz .LBB0_336
	v_mul_f32_e32 v113, 0xbfb8aa3b, v92
	v_mul_f32_e32 v114, 0xbfb8aa3b, v89
	v_exp_f32_e32 v113, v113
	v_exp_f32_e32 v114, v114
	v_mul_f32_e32 v115, 0xbfb8aa3b, v90
	v_mul_f32_e32 v117, 0xbfb8aa3b, v94
	v_add_f32_e32 v113, 1.0, v113
	v_rcp_f32_e32 v116, v113
	v_add_f32_e32 v113, 1.0, v114
	v_mul_f32_e32 v114, 0xbfb8aa3b, v93
	v_exp_f32_e32 v114, v114
	v_exp_f32_e32 v115, v115
	v_exp_f32_e32 v117, v117
	v_mul_f32_e32 v112, 0xbfb8aa3b, v88
	v_add_f32_e32 v126, 1.0, v114
	v_add_f32_e32 v114, 1.0, v115
	v_add_f32_e32 v115, 1.0, v117
	v_mul_f32_e32 v117, 0xbfb8aa3b, v91
	v_mul_f32_e32 v118, 0xbfb8aa3b, v95
	v_exp_f32_e32 v112, v112
	v_exp_f32_e32 v117, v117
	v_exp_f32_e32 v119, v118
	v_rcp_f32_e32 v118, v115
	v_add_f32_e32 v112, 1.0, v112
	v_add_f32_e32 v115, 1.0, v117
	v_add_f32_e32 v117, 1.0, v119
	v_rcp_f32_e32 v112, v112
	v_rcp_f32_e32 v113, v113
	v_rcp_f32_e32 v114, v114
	v_rcp_f32_e32 v115, v115
	v_rcp_f32_e32 v119, v117
	v_rcp_f32_e32 v117, v126
	v_pk_mul_f32 v[112:113], v[88:89], v[112:113]
	v_pk_mul_f32 v[114:115], v[90:91], v[114:115]
	v_pk_mul_f32 v[118:119], v[94:95], v[118:119]
	v_pk_mul_f32 v[116:117], v[92:93], v[116:117]
.LBB0_336:
	v_or_b32_e32 v126, 32, v163
	v_add_u32_e32 v126, s9, v126
	v_ashrrev_i32_e32 v127, 31, v126
	v_lshlrev_b64 v[126:127], 12, v[126:127]
	v_lshl_add_u64 v[126:127], v[124:125], 0, v[126:127]
	v_cvt_pk_bf16_f32 v112, v112, v113
	v_cvt_pk_bf16_f32 v113, v114, v115
	v_cvt_pk_bf16_f32 v114, v116, v117
	v_cvt_pk_bf16_f32 v115, v118, v119
	global_store_dwordx4 v[126:127], v[112:115], off nt
	v_mov_b64_e32 v[118:119], v[86:87]
	s_and_b64 vcc, exec, s[6:7]
	v_mov_b64_e32 v[114:115], v[82:83]
	v_mov_b64_e32 v[112:113], v[80:81]
	v_mov_b64_e32 v[116:117], v[84:85]
	s_cbranch_vccnz .LBB0_338
	v_mul_f32_e32 v113, 0xbfb8aa3b, v84
	v_mul_f32_e32 v114, 0xbfb8aa3b, v81
	v_exp_f32_e32 v113, v113
	v_exp_f32_e32 v114, v114
	v_mul_f32_e32 v115, 0xbfb8aa3b, v82
	v_mul_f32_e32 v117, 0xbfb8aa3b, v86
	v_add_f32_e32 v113, 1.0, v113
	v_rcp_f32_e32 v116, v113
	v_add_f32_e32 v113, 1.0, v114
	v_mul_f32_e32 v114, 0xbfb8aa3b, v85
	v_exp_f32_e32 v114, v114
	v_exp_f32_e32 v115, v115
	v_exp_f32_e32 v117, v117
	v_mul_f32_e32 v112, 0xbfb8aa3b, v80
	v_add_f32_e32 v132, 1.0, v114
	v_add_f32_e32 v114, 1.0, v115
	v_add_f32_e32 v115, 1.0, v117
	v_mul_f32_e32 v117, 0xbfb8aa3b, v83
	v_mul_f32_e32 v118, 0xbfb8aa3b, v87
	v_exp_f32_e32 v112, v112
	v_exp_f32_e32 v117, v117
	v_exp_f32_e32 v119, v118
	v_rcp_f32_e32 v118, v115
	v_add_f32_e32 v112, 1.0, v112
	v_add_f32_e32 v115, 1.0, v117
	v_add_f32_e32 v117, 1.0, v119
	v_rcp_f32_e32 v112, v112
	v_rcp_f32_e32 v113, v113
	v_rcp_f32_e32 v114, v114
	v_rcp_f32_e32 v115, v115
	v_rcp_f32_e32 v119, v117
	v_rcp_f32_e32 v117, v132
	v_pk_mul_f32 v[112:113], v[80:81], v[112:113]
	v_pk_mul_f32 v[114:115], v[82:83], v[114:115]
	v_pk_mul_f32 v[118:119], v[86:87], v[118:119]
	v_pk_mul_f32 v[116:117], v[84:85], v[116:117]
.LBB0_338:
	v_cvt_pk_bf16_f32 v112, v112, v113
	v_cvt_pk_bf16_f32 v113, v114, v115
	s_nop 0
	v_cvt_pk_bf16_f32 v114, v116, v117
	v_cvt_pk_bf16_f32 v115, v118, v119
	global_store_dwordx4 v[126:127], v[112:115], off offset:256 nt
	v_mov_b64_e32 v[118:119], v[78:79]
	s_and_b64 vcc, exec, s[6:7]
	v_mov_b64_e32 v[114:115], v[74:75]
	v_mov_b64_e32 v[112:113], v[72:73]
	v_mov_b64_e32 v[116:117], v[76:77]
	s_cbranch_vccnz .LBB0_340
	v_mul_f32_e32 v113, 0xbfb8aa3b, v76
	v_mul_f32_e32 v114, 0xbfb8aa3b, v73
	v_exp_f32_e32 v113, v113
	v_exp_f32_e32 v114, v114
	v_mul_f32_e32 v115, 0xbfb8aa3b, v74
	v_mul_f32_e32 v117, 0xbfb8aa3b, v78
	v_add_f32_e32 v113, 1.0, v113
	v_rcp_f32_e32 v116, v113
	v_add_f32_e32 v113, 1.0, v114
	v_mul_f32_e32 v114, 0xbfb8aa3b, v77
	v_exp_f32_e32 v114, v114
	v_exp_f32_e32 v115, v115
	v_exp_f32_e32 v117, v117
	v_mul_f32_e32 v112, 0xbfb8aa3b, v72
	v_add_f32_e32 v126, 1.0, v114
	v_add_f32_e32 v114, 1.0, v115
	v_add_f32_e32 v115, 1.0, v117
	v_mul_f32_e32 v117, 0xbfb8aa3b, v75
	v_mul_f32_e32 v118, 0xbfb8aa3b, v79
	v_exp_f32_e32 v112, v112
	v_exp_f32_e32 v117, v117
	v_exp_f32_e32 v119, v118
	v_rcp_f32_e32 v118, v115
	v_add_f32_e32 v112, 1.0, v112
	v_add_f32_e32 v115, 1.0, v117
	v_add_f32_e32 v117, 1.0, v119
	v_rcp_f32_e32 v112, v112
	v_rcp_f32_e32 v113, v113
	v_rcp_f32_e32 v114, v114
	v_rcp_f32_e32 v115, v115
	v_rcp_f32_e32 v119, v117
	v_rcp_f32_e32 v117, v126
	v_pk_mul_f32 v[112:113], v[72:73], v[112:113]
	v_pk_mul_f32 v[114:115], v[74:75], v[114:115]
	v_pk_mul_f32 v[118:119], v[78:79], v[118:119]
	v_pk_mul_f32 v[116:117], v[76:77], v[116:117]
.LBB0_340:
	v_or_b32_e32 v126, 48, v163
	v_add_u32_e32 v126, s9, v126
	v_ashrrev_i32_e32 v127, 31, v126
	v_lshlrev_b64 v[126:127], 12, v[126:127]
	v_lshl_add_u64 v[126:127], v[124:125], 0, v[126:127]
	v_cvt_pk_bf16_f32 v112, v112, v113
	v_cvt_pk_bf16_f32 v113, v114, v115
	v_cvt_pk_bf16_f32 v114, v116, v117
	v_cvt_pk_bf16_f32 v115, v118, v119
	global_store_dwordx4 v[126:127], v[112:115], off nt
	v_mov_b64_e32 v[118:119], v[70:71]
	s_and_b64 vcc, exec, s[6:7]
	v_mov_b64_e32 v[114:115], v[66:67]
	v_mov_b64_e32 v[112:113], v[64:65]
	v_mov_b64_e32 v[116:117], v[68:69]
	s_cbranch_vccnz .LBB0_342
	v_mul_f32_e32 v113, 0xbfb8aa3b, v68
	v_mul_f32_e32 v114, 0xbfb8aa3b, v65
	v_exp_f32_e32 v113, v113
	v_exp_f32_e32 v114, v114
	v_mul_f32_e32 v115, 0xbfb8aa3b, v66
	v_mul_f32_e32 v117, 0xbfb8aa3b, v70
	v_add_f32_e32 v113, 1.0, v113
	v_rcp_f32_e32 v116, v113
	v_add_f32_e32 v113, 1.0, v114
	v_mul_f32_e32 v114, 0xbfb8aa3b, v69
	v_exp_f32_e32 v114, v114
	v_exp_f32_e32 v115, v115
	v_exp_f32_e32 v117, v117
	v_mul_f32_e32 v112, 0xbfb8aa3b, v64
	v_add_f32_e32 v132, 1.0, v114
	v_add_f32_e32 v114, 1.0, v115
	v_add_f32_e32 v115, 1.0, v117
	v_mul_f32_e32 v117, 0xbfb8aa3b, v67
	v_mul_f32_e32 v118, 0xbfb8aa3b, v71
	v_exp_f32_e32 v112, v112
	v_exp_f32_e32 v117, v117
	v_exp_f32_e32 v119, v118
	v_rcp_f32_e32 v118, v115
	v_add_f32_e32 v112, 1.0, v112
	v_add_f32_e32 v115, 1.0, v117
	v_add_f32_e32 v117, 1.0, v119
	v_rcp_f32_e32 v112, v112
	v_rcp_f32_e32 v113, v113
	v_rcp_f32_e32 v114, v114
	v_rcp_f32_e32 v115, v115
	v_rcp_f32_e32 v119, v117
	v_rcp_f32_e32 v117, v132
	v_pk_mul_f32 v[112:113], v[64:65], v[112:113]
	v_pk_mul_f32 v[114:115], v[66:67], v[114:115]
	v_pk_mul_f32 v[118:119], v[70:71], v[118:119]
	v_pk_mul_f32 v[116:117], v[68:69], v[116:117]
.LBB0_342:
	v_cvt_pk_bf16_f32 v112, v112, v113
	v_cvt_pk_bf16_f32 v113, v114, v115
	s_nop 0
	v_cvt_pk_bf16_f32 v114, v116, v117
	v_cvt_pk_bf16_f32 v115, v118, v119
	global_store_dwordx4 v[126:127], v[112:115], off offset:256 nt
	v_mov_b64_e32 v[118:119], v[62:63]
	s_and_b64 vcc, exec, s[6:7]
	v_mov_b64_e32 v[114:115], v[58:59]
	v_mov_b64_e32 v[112:113], v[56:57]
	v_mov_b64_e32 v[116:117], v[60:61]
	s_cbranch_vccnz .LBB0_344
	v_mul_f32_e32 v113, 0xbfb8aa3b, v60
	v_mul_f32_e32 v114, 0xbfb8aa3b, v57
	v_exp_f32_e32 v113, v113
	v_exp_f32_e32 v114, v114
	v_mul_f32_e32 v115, 0xbfb8aa3b, v58
	v_mul_f32_e32 v117, 0xbfb8aa3b, v62
	v_add_f32_e32 v113, 1.0, v113
	v_rcp_f32_e32 v116, v113
	v_add_f32_e32 v113, 1.0, v114
	v_mul_f32_e32 v114, 0xbfb8aa3b, v61
	v_exp_f32_e32 v114, v114
	v_exp_f32_e32 v115, v115
	v_exp_f32_e32 v117, v117
	v_mul_f32_e32 v112, 0xbfb8aa3b, v56
	v_add_f32_e32 v126, 1.0, v114
	v_add_f32_e32 v114, 1.0, v115
	v_add_f32_e32 v115, 1.0, v117
	v_mul_f32_e32 v117, 0xbfb8aa3b, v59
	v_mul_f32_e32 v118, 0xbfb8aa3b, v63
	v_exp_f32_e32 v112, v112
	v_exp_f32_e32 v117, v117
	v_exp_f32_e32 v119, v118
	v_rcp_f32_e32 v118, v115
	v_add_f32_e32 v112, 1.0, v112
	v_add_f32_e32 v115, 1.0, v117
	v_add_f32_e32 v117, 1.0, v119
	v_rcp_f32_e32 v112, v112
	v_rcp_f32_e32 v113, v113
	v_rcp_f32_e32 v114, v114
	v_rcp_f32_e32 v115, v115
	v_rcp_f32_e32 v119, v117
	v_rcp_f32_e32 v117, v126
	v_pk_mul_f32 v[112:113], v[56:57], v[112:113]
	v_pk_mul_f32 v[114:115], v[58:59], v[114:115]
	v_pk_mul_f32 v[118:119], v[62:63], v[118:119]
	v_pk_mul_f32 v[116:117], v[60:61], v[116:117]
.LBB0_344:
	v_add_u32_e32 v126, s9, v181
	v_ashrrev_i32_e32 v127, 31, v126
	v_lshlrev_b64 v[126:127], 12, v[126:127]
	v_lshl_add_u64 v[126:127], v[124:125], 0, v[126:127]
	v_cvt_pk_bf16_f32 v112, v112, v113
	v_cvt_pk_bf16_f32 v113, v114, v115
	v_cvt_pk_bf16_f32 v114, v116, v117
	v_cvt_pk_bf16_f32 v115, v118, v119
	global_store_dwordx4 v[126:127], v[112:115], off nt
	v_mov_b64_e32 v[118:119], v[54:55]
	s_and_b64 vcc, exec, s[6:7]
	v_mov_b64_e32 v[114:115], v[50:51]
	v_mov_b64_e32 v[112:113], v[48:49]
	v_mov_b64_e32 v[116:117], v[52:53]
	s_cbranch_vccnz .LBB0_346
	v_mul_f32_e32 v113, 0xbfb8aa3b, v52
	v_mul_f32_e32 v114, 0xbfb8aa3b, v49
	v_exp_f32_e32 v113, v113
	v_exp_f32_e32 v114, v114
	v_mul_f32_e32 v115, 0xbfb8aa3b, v50
	v_mul_f32_e32 v117, 0xbfb8aa3b, v54
	v_add_f32_e32 v113, 1.0, v113
	v_rcp_f32_e32 v116, v113
	v_add_f32_e32 v113, 1.0, v114
	v_mul_f32_e32 v114, 0xbfb8aa3b, v53
	v_exp_f32_e32 v114, v114
	v_exp_f32_e32 v115, v115
	v_exp_f32_e32 v117, v117
	v_mul_f32_e32 v112, 0xbfb8aa3b, v48
	v_add_f32_e32 v132, 1.0, v114
	v_add_f32_e32 v114, 1.0, v115
	v_add_f32_e32 v115, 1.0, v117
	v_mul_f32_e32 v117, 0xbfb8aa3b, v51
	v_mul_f32_e32 v118, 0xbfb8aa3b, v55
	v_exp_f32_e32 v112, v112
	v_exp_f32_e32 v117, v117
	v_exp_f32_e32 v119, v118
	v_rcp_f32_e32 v118, v115
	v_add_f32_e32 v112, 1.0, v112
	v_add_f32_e32 v115, 1.0, v117
	v_add_f32_e32 v117, 1.0, v119
	v_rcp_f32_e32 v112, v112
	v_rcp_f32_e32 v113, v113
	v_rcp_f32_e32 v114, v114
	v_rcp_f32_e32 v115, v115
	v_rcp_f32_e32 v119, v117
	v_rcp_f32_e32 v117, v132
	v_pk_mul_f32 v[112:113], v[48:49], v[112:113]
	v_pk_mul_f32 v[114:115], v[50:51], v[114:115]
	v_pk_mul_f32 v[118:119], v[54:55], v[118:119]
	v_pk_mul_f32 v[116:117], v[52:53], v[116:117]
.LBB0_346:
	v_cvt_pk_bf16_f32 v112, v112, v113
	v_cvt_pk_bf16_f32 v113, v114, v115
	s_nop 0
	v_cvt_pk_bf16_f32 v114, v116, v117
	v_cvt_pk_bf16_f32 v115, v118, v119
	global_store_dwordx4 v[126:127], v[112:115], off offset:256 nt
	v_mov_b64_e32 v[118:119], v[46:47]
	s_and_b64 vcc, exec, s[6:7]
	v_mov_b64_e32 v[114:115], v[42:43]
	v_mov_b64_e32 v[112:113], v[40:41]
	v_mov_b64_e32 v[116:117], v[44:45]
	s_cbranch_vccnz .LBB0_348
	v_mul_f32_e32 v113, 0xbfb8aa3b, v44
	v_mul_f32_e32 v114, 0xbfb8aa3b, v41
	v_exp_f32_e32 v113, v113
	v_exp_f32_e32 v114, v114
	v_mul_f32_e32 v115, 0xbfb8aa3b, v42
	v_mul_f32_e32 v117, 0xbfb8aa3b, v46
	v_add_f32_e32 v113, 1.0, v113
	v_rcp_f32_e32 v116, v113
	v_add_f32_e32 v113, 1.0, v114
	v_mul_f32_e32 v114, 0xbfb8aa3b, v45
	v_exp_f32_e32 v114, v114
	v_exp_f32_e32 v115, v115
	v_exp_f32_e32 v117, v117
	v_mul_f32_e32 v112, 0xbfb8aa3b, v40
	v_add_f32_e32 v126, 1.0, v114
	v_add_f32_e32 v114, 1.0, v115
	v_add_f32_e32 v115, 1.0, v117
	v_mul_f32_e32 v117, 0xbfb8aa3b, v43
	v_mul_f32_e32 v118, 0xbfb8aa3b, v47
	v_exp_f32_e32 v112, v112
	v_exp_f32_e32 v117, v117
	v_exp_f32_e32 v119, v118
	v_rcp_f32_e32 v118, v115
	v_add_f32_e32 v112, 1.0, v112
	v_add_f32_e32 v115, 1.0, v117
	v_add_f32_e32 v117, 1.0, v119
	v_rcp_f32_e32 v112, v112
	v_rcp_f32_e32 v113, v113
	v_rcp_f32_e32 v114, v114
	v_rcp_f32_e32 v115, v115
	v_rcp_f32_e32 v119, v117
	v_rcp_f32_e32 v117, v126
	v_pk_mul_f32 v[112:113], v[40:41], v[112:113]
	v_pk_mul_f32 v[114:115], v[42:43], v[114:115]
	v_pk_mul_f32 v[118:119], v[46:47], v[118:119]
	v_pk_mul_f32 v[116:117], v[44:45], v[116:117]
.LBB0_348:
	v_add_u32_e32 v126, s9, v182
	v_ashrrev_i32_e32 v127, 31, v126
	v_lshlrev_b64 v[126:127], 12, v[126:127]
	v_lshl_add_u64 v[126:127], v[124:125], 0, v[126:127]
	v_cvt_pk_bf16_f32 v112, v112, v113
	v_cvt_pk_bf16_f32 v113, v114, v115
	v_cvt_pk_bf16_f32 v114, v116, v117
	v_cvt_pk_bf16_f32 v115, v118, v119
	global_store_dwordx4 v[126:127], v[112:115], off nt
	v_mov_b64_e32 v[118:119], v[38:39]
	s_and_b64 vcc, exec, s[6:7]
	v_mov_b64_e32 v[114:115], v[34:35]
	v_mov_b64_e32 v[112:113], v[32:33]
	v_mov_b64_e32 v[116:117], v[36:37]
	s_cbranch_vccnz .LBB0_350
	v_mul_f32_e32 v113, 0xbfb8aa3b, v36
	v_mul_f32_e32 v114, 0xbfb8aa3b, v33
	v_exp_f32_e32 v113, v113
	v_exp_f32_e32 v114, v114
	v_mul_f32_e32 v115, 0xbfb8aa3b, v34
	v_mul_f32_e32 v117, 0xbfb8aa3b, v38
	v_add_f32_e32 v113, 1.0, v113
	v_rcp_f32_e32 v116, v113
	v_add_f32_e32 v113, 1.0, v114
	v_mul_f32_e32 v114, 0xbfb8aa3b, v37
	v_exp_f32_e32 v114, v114
	v_exp_f32_e32 v115, v115
	v_exp_f32_e32 v117, v117
	v_mul_f32_e32 v112, 0xbfb8aa3b, v32
	v_add_f32_e32 v132, 1.0, v114
	v_add_f32_e32 v114, 1.0, v115
	v_add_f32_e32 v115, 1.0, v117
	v_mul_f32_e32 v117, 0xbfb8aa3b, v35
	v_mul_f32_e32 v118, 0xbfb8aa3b, v39
	v_exp_f32_e32 v112, v112
	v_exp_f32_e32 v117, v117
	v_exp_f32_e32 v119, v118
	v_rcp_f32_e32 v118, v115
	v_add_f32_e32 v112, 1.0, v112
	v_add_f32_e32 v115, 1.0, v117
	v_add_f32_e32 v117, 1.0, v119
	v_rcp_f32_e32 v112, v112
	v_rcp_f32_e32 v113, v113
	v_rcp_f32_e32 v114, v114
	v_rcp_f32_e32 v115, v115
	v_rcp_f32_e32 v119, v117
	v_rcp_f32_e32 v117, v132
	v_pk_mul_f32 v[112:113], v[32:33], v[112:113]
	v_pk_mul_f32 v[114:115], v[34:35], v[114:115]
	v_pk_mul_f32 v[118:119], v[38:39], v[118:119]
	v_pk_mul_f32 v[116:117], v[36:37], v[116:117]
.LBB0_350:
	v_cvt_pk_bf16_f32 v112, v112, v113
	v_cvt_pk_bf16_f32 v113, v114, v115
	s_nop 0
	v_cvt_pk_bf16_f32 v114, v116, v117
	v_cvt_pk_bf16_f32 v115, v118, v119
	global_store_dwordx4 v[126:127], v[112:115], off offset:256 nt
	v_mov_b64_e32 v[118:119], v[30:31]
	s_and_b64 vcc, exec, s[6:7]
	v_mov_b64_e32 v[114:115], v[26:27]
	v_mov_b64_e32 v[112:113], v[24:25]
	v_mov_b64_e32 v[116:117], v[28:29]
	s_cbranch_vccnz .LBB0_352
	v_mul_f32_e32 v113, 0xbfb8aa3b, v28
	v_mul_f32_e32 v114, 0xbfb8aa3b, v25
	v_exp_f32_e32 v113, v113
	v_exp_f32_e32 v114, v114
	v_mul_f32_e32 v115, 0xbfb8aa3b, v26
	v_mul_f32_e32 v117, 0xbfb8aa3b, v30
	v_add_f32_e32 v113, 1.0, v113
	v_rcp_f32_e32 v116, v113
	v_add_f32_e32 v113, 1.0, v114
	v_mul_f32_e32 v114, 0xbfb8aa3b, v29
	v_exp_f32_e32 v114, v114
	v_exp_f32_e32 v115, v115
	v_exp_f32_e32 v117, v117
	v_mul_f32_e32 v112, 0xbfb8aa3b, v24
	v_add_f32_e32 v126, 1.0, v114
	v_add_f32_e32 v114, 1.0, v115
	v_add_f32_e32 v115, 1.0, v117
	v_mul_f32_e32 v117, 0xbfb8aa3b, v27
	v_mul_f32_e32 v118, 0xbfb8aa3b, v31
	v_exp_f32_e32 v112, v112
	v_exp_f32_e32 v117, v117
	v_exp_f32_e32 v119, v118
	v_rcp_f32_e32 v118, v115
	v_add_f32_e32 v112, 1.0, v112
	v_add_f32_e32 v115, 1.0, v117
	v_add_f32_e32 v117, 1.0, v119
	v_rcp_f32_e32 v112, v112
	v_rcp_f32_e32 v113, v113
	v_rcp_f32_e32 v114, v114
	v_rcp_f32_e32 v115, v115
	v_rcp_f32_e32 v119, v117
	v_rcp_f32_e32 v117, v126
	v_pk_mul_f32 v[112:113], v[24:25], v[112:113]
	v_pk_mul_f32 v[114:115], v[26:27], v[114:115]
	v_pk_mul_f32 v[118:119], v[30:31], v[118:119]
	v_pk_mul_f32 v[116:117], v[28:29], v[116:117]
.LBB0_352:
	v_add_u32_e32 v126, s9, v183
	v_ashrrev_i32_e32 v127, 31, v126
	v_lshlrev_b64 v[126:127], 12, v[126:127]
	v_lshl_add_u64 v[126:127], v[124:125], 0, v[126:127]
	v_cvt_pk_bf16_f32 v112, v112, v113
	v_cvt_pk_bf16_f32 v113, v114, v115
	v_cvt_pk_bf16_f32 v114, v116, v117
	v_cvt_pk_bf16_f32 v115, v118, v119
	global_store_dwordx4 v[126:127], v[112:115], off nt
	v_mov_b64_e32 v[118:119], v[22:23]
	s_and_b64 vcc, exec, s[6:7]
	v_mov_b64_e32 v[114:115], v[18:19]
	v_mov_b64_e32 v[112:113], v[16:17]
	v_mov_b64_e32 v[116:117], v[20:21]
	s_cbranch_vccnz .LBB0_354
	v_mul_f32_e32 v113, 0xbfb8aa3b, v20
	v_mul_f32_e32 v114, 0xbfb8aa3b, v17
	v_exp_f32_e32 v113, v113
	v_exp_f32_e32 v114, v114
	v_mul_f32_e32 v115, 0xbfb8aa3b, v18
	v_mul_f32_e32 v117, 0xbfb8aa3b, v22
	v_add_f32_e32 v113, 1.0, v113
	v_rcp_f32_e32 v116, v113
	v_add_f32_e32 v113, 1.0, v114
	v_mul_f32_e32 v114, 0xbfb8aa3b, v21
	v_exp_f32_e32 v114, v114
	v_exp_f32_e32 v115, v115
	v_exp_f32_e32 v117, v117
	v_mul_f32_e32 v112, 0xbfb8aa3b, v16
	v_add_f32_e32 v132, 1.0, v114
	v_add_f32_e32 v114, 1.0, v115
	v_add_f32_e32 v115, 1.0, v117
	v_mul_f32_e32 v117, 0xbfb8aa3b, v19
	v_mul_f32_e32 v118, 0xbfb8aa3b, v23
	v_exp_f32_e32 v112, v112
	v_exp_f32_e32 v117, v117
	v_exp_f32_e32 v119, v118
	v_rcp_f32_e32 v118, v115
	v_add_f32_e32 v112, 1.0, v112
	v_add_f32_e32 v115, 1.0, v117
	v_add_f32_e32 v117, 1.0, v119
	v_rcp_f32_e32 v112, v112
	v_rcp_f32_e32 v113, v113
	v_rcp_f32_e32 v114, v114
	v_rcp_f32_e32 v115, v115
	v_rcp_f32_e32 v119, v117
	v_rcp_f32_e32 v117, v132
	v_pk_mul_f32 v[112:113], v[16:17], v[112:113]
	v_pk_mul_f32 v[114:115], v[18:19], v[114:115]
	v_pk_mul_f32 v[118:119], v[22:23], v[118:119]
	v_pk_mul_f32 v[116:117], v[20:21], v[116:117]
.LBB0_354:
	v_cvt_pk_bf16_f32 v112, v112, v113
	v_cvt_pk_bf16_f32 v113, v114, v115
	s_nop 0
	v_cvt_pk_bf16_f32 v114, v116, v117
	v_cvt_pk_bf16_f32 v115, v118, v119
	global_store_dwordx4 v[126:127], v[112:115], off offset:256 nt
	v_mov_b64_e32 v[118:119], v[10:11]
	s_and_b64 vcc, exec, s[6:7]
	v_mov_b64_e32 v[114:115], v[14:15]
	v_mov_b64_e32 v[112:113], v[12:13]
	v_mov_b64_e32 v[116:117], v[8:9]
	s_cbranch_vccnz .LBB0_356
	v_mul_f32_e32 v113, 0xbfb8aa3b, v8
	v_mul_f32_e32 v114, 0xbfb8aa3b, v13
	v_exp_f32_e32 v113, v113
	v_exp_f32_e32 v114, v114
	v_mul_f32_e32 v115, 0xbfb8aa3b, v14
	v_mul_f32_e32 v117, 0xbfb8aa3b, v10
	v_add_f32_e32 v113, 1.0, v113
	v_rcp_f32_e32 v116, v113
	v_add_f32_e32 v113, 1.0, v114
	v_mul_f32_e32 v114, 0xbfb8aa3b, v9
	v_exp_f32_e32 v114, v114
	v_exp_f32_e32 v115, v115
	v_exp_f32_e32 v117, v117
	v_mul_f32_e32 v112, 0xbfb8aa3b, v12
	v_add_f32_e32 v126, 1.0, v114
	v_add_f32_e32 v114, 1.0, v115
	v_add_f32_e32 v115, 1.0, v117
	v_mul_f32_e32 v117, 0xbfb8aa3b, v15
	v_mul_f32_e32 v118, 0xbfb8aa3b, v11
	v_exp_f32_e32 v112, v112
	v_exp_f32_e32 v117, v117
	v_exp_f32_e32 v119, v118
	v_rcp_f32_e32 v118, v115
	v_add_f32_e32 v112, 1.0, v112
	v_add_f32_e32 v115, 1.0, v117
	v_add_f32_e32 v117, 1.0, v119
	v_rcp_f32_e32 v112, v112
	v_rcp_f32_e32 v113, v113
	v_rcp_f32_e32 v114, v114
	v_rcp_f32_e32 v115, v115
	v_rcp_f32_e32 v119, v117
	v_rcp_f32_e32 v117, v126
	v_pk_mul_f32 v[112:113], v[12:13], v[112:113]
	v_pk_mul_f32 v[114:115], v[14:15], v[114:115]
	v_pk_mul_f32 v[118:119], v[10:11], v[118:119]
	v_pk_mul_f32 v[116:117], v[8:9], v[116:117]
.LBB0_356:
	v_add_u32_e32 v126, s9, v184
	v_ashrrev_i32_e32 v127, 31, v126
	v_lshlrev_b64 v[126:127], 12, v[126:127]
	v_lshl_add_u64 v[174:175], v[124:125], 0, v[126:127]
	v_cvt_pk_bf16_f32 v112, v112, v113
	v_cvt_pk_bf16_f32 v113, v114, v115
	v_cvt_pk_bf16_f32 v114, v116, v117
	v_cvt_pk_bf16_f32 v115, v118, v119
	global_store_dwordx4 v[174:175], v[112:115], off nt
	v_mov_b64_e32 v[118:119], v[2:3]
	s_and_b64 vcc, exec, s[6:7]
	v_mov_b64_e32 v[114:115], v[6:7]
	v_mov_b64_e32 v[112:113], v[4:5]
	v_mov_b64_e32 v[116:117], v[0:1]
	s_cbranch_vccnz .LBB0_358
	v_mul_f32_e32 v113, 0xbfb8aa3b, v0
	v_mul_f32_e32 v114, 0xbfb8aa3b, v5
	v_exp_f32_e32 v113, v113
	v_exp_f32_e32 v114, v114
	v_mul_f32_e32 v115, 0xbfb8aa3b, v6
	v_mul_f32_e32 v117, 0xbfb8aa3b, v2
	v_add_f32_e32 v113, 1.0, v113
	v_rcp_f32_e32 v116, v113
	v_add_f32_e32 v113, 1.0, v114
	v_mul_f32_e32 v114, 0xbfb8aa3b, v1
	v_exp_f32_e32 v114, v114
	v_exp_f32_e32 v115, v115
	v_exp_f32_e32 v117, v117
	v_mul_f32_e32 v112, 0xbfb8aa3b, v4
	v_add_f32_e32 v124, 1.0, v114
	v_add_f32_e32 v114, 1.0, v115
	v_add_f32_e32 v115, 1.0, v117
	v_mul_f32_e32 v117, 0xbfb8aa3b, v7
	v_mul_f32_e32 v118, 0xbfb8aa3b, v3
	v_exp_f32_e32 v112, v112
	v_exp_f32_e32 v117, v117
	v_exp_f32_e32 v119, v118
	v_rcp_f32_e32 v118, v115
	v_add_f32_e32 v112, 1.0, v112
	v_add_f32_e32 v115, 1.0, v117
	v_add_f32_e32 v117, 1.0, v119
	v_rcp_f32_e32 v112, v112
	v_rcp_f32_e32 v113, v113
	v_rcp_f32_e32 v114, v114
	v_rcp_f32_e32 v115, v115
	v_rcp_f32_e32 v119, v117
	v_rcp_f32_e32 v117, v124
	v_pk_mul_f32 v[112:113], v[4:5], v[112:113]
	v_pk_mul_f32 v[114:115], v[6:7], v[114:115]
	v_pk_mul_f32 v[118:119], v[2:3], v[118:119]
	v_pk_mul_f32 v[116:117], v[0:1], v[116:117]

.LBB0_395:
	v_cvt_pk_bf16_f32 v148, v148, v149
	v_cvt_pk_bf16_f32 v149, v144, v145
	v_cvt_pk_bf16_f32 v150, v150, v151
	s_nop 0
	v_cvt_pk_bf16_f32 v151, v146, v147
	ds_read_b128 v[204:207], v192 offset:16
	s_and_b64 s[8:9], s[8:9], exec
	v_readlane_b32 s72, v254, 16
	s_cselect_b32 s8, s61, 0xe000000
	v_readlane_b32 s78, v254, 22
	v_readlane_b32 s79, v254, 23
	s_add_u32 s8, s78, s8
	s_addc_u32 s9, s79, 0
	s_lshl_b32 s27, s27, 1
	s_add_u32 s8, s8, s27
	s_waitcnt lgkmcnt(0)
	v_mov_b32_e32 v146, v205
	v_mov_b32_e32 v147, v206
	v_mov_b32_e32 v205, v207
	s_addc_u32 s9, s9, 0
	s_lshl_b32 s27, s52, 1
	v_pk_add_f32 v[146:147], v[146:147], v[204:205]
	s_add_u32 s8, s8, s27
	v_add_f32_e32 v146, v146, v147
	s_addc_u32 s9, s9, 0
	v_lshlrev_b32_e32 v160, 1, v162
	v_fmamk_f32 v146, v146, 0x3c000000, v202
	v_lshl_add_u64 v[144:145], s[8:9], 0, v[160:161]
	v_rsq_f32_e32 v160, v146
	v_lshlrev_b64 v[146:147], 12, v[174:175]
	v_lshl_add_u64 v[146:147], v[144:145], 0, v[146:147]
	global_store_dwordx4 v[146:147], v[148:151], off nt
	s_and_b64 vcc, exec, s[6:7]
	v_readlane_b32 s73, v254, 17
	v_mul_f32_e32 v150, v203, v160
	v_pk_mul_f32 v[148:149], v[120:121], v[150:151] op_sel_hi:[1,0]
	v_pk_mul_f32 v[120:121], v[122:123], v[150:151] op_sel_hi:[1,0]
	v_pk_mul_f32 v[128:129], v[128:129], v[150:151] op_sel_hi:[1,0]
	v_pk_mul_f32 v[122:123], v[130:131], v[150:151] op_sel_hi:[1,0]
	v_pk_mul_f32 v[120:121], v[118:119], v[120:121]
	v_pk_mul_f32 v[148:149], v[116:117], v[148:149]
	v_pk_mul_f32 v[122:123], v[114:115], v[122:123]
	v_pk_mul_f32 v[128:129], v[112:113], v[128:129]
	v_readlane_b32 s74, v254, 18
	v_readlane_b32 s75, v254, 19
	v_readlane_b32 s76, v254, 20
	v_readlane_b32 s77, v254, 21
	s_cbranch_vccnz .LBB0_397
	v_mov_b32_e32 v130, v148
	v_mov_b32_e32 v150, v148
	v_mov_b32_e32 v160, v128
	v_mov_b32_e32 v174, v128
	v_permlane32_swap_b32_e32 v130, v150
	s_nop 0
	v_permlane32_swap_b32_e32 v160, v174
	v_mov_b32_e32 v131, v149
	v_mov_b32_e32 v151, v149
	v_mov_b32_e32 v175, v129
	v_mov_b32_e32 v186, v129
	v_cndmask_b32_e64 v130, v130, v150, s[2:3]
	v_cndmask_b32_e64 v150, v160, v174, s[2:3]
	v_mov_b32_e32 v160, v120
	v_mov_b32_e32 v174, v120
	v_permlane32_swap_b32_e32 v131, v151
	v_permlane32_swap_b32_e32 v175, v186
	v_permlane32_swap_b32_e32 v160, v174
	v_cndmask_b32_e64 v131, v131, v151, s[2:3]
	v_cndmask_b32_e64 v151, v175, v186, s[2:3]
	v_cndmask_b32_e64 v160, v160, v174, s[2:3]
	v_mov_b32_e32 v174, v122
	v_mov_b32_e32 v175, v122
	s_nop 1
	v_permlane32_swap_b32_e32 v174, v175
	v_cndmask_b32_e64 v175, v174, v175, s[2:3]
	v_mul_f32_e32 v174, v138, v160
	v_mul_f32_e32 v186, v142, v175
	v_mov_b32_e32 v160, v121
	v_mov_b32_e32 v175, v121
	s_nop 1
	v_permlane32_swap_b32_e32 v160, v175
	v_cndmask_b32_e64 v189, v160, v175, s[2:3]
	v_mov_b32_e32 v160, v123
	v_mov_b32_e32 v175, v123
	v_pk_mul_f32 v[148:149], v[132:133], v[148:149]
	s_nop 0
	v_permlane32_swap_b32_e32 v160, v175
	v_cndmask_b32_e64 v205, v160, v175, s[2:3]
	v_mov_b32_e32 v206, v135
	v_mov_b32_e32 v207, v139
	v_mov_b32_e32 v188, v121
	v_pk_fma_f32 v[148:149], v[136:137], v[130:131], v[148:149]
	v_mov_b32_e32 v130, v127
	v_mov_b32_e32 v131, v143
	v_mov_b32_e32 v204, v123
	v_pk_mul_f32 v[188:189], v[206:207], v[188:189]
	v_pk_mul_f32 v[130:131], v[130:131], v[204:205]
	v_pk_mul_f32 v[128:129], v[124:125], v[128:129]
	v_mul_f32_e32 v120, v134, v120
	v_mul_f32_e32 v122, v126, v122
	v_mov_b32_e32 v121, v188
	v_mov_b32_e32 v175, v189
	v_mov_b32_e32 v123, v130
	v_mov_b32_e32 v187, v131
	v_pk_add_f32 v[120:121], v[120:121], v[174:175]
	v_pk_fma_f32 v[128:129], v[140:141], v[150:151], v[128:129]
	v_pk_add_f32 v[122:123], v[122:123], v[186:187]
.LBB0_397:
	v_cvt_pk_bf16_f32 v148, v148, v149
	v_cvt_pk_bf16_f32 v149, v120, v121
	v_or_b32_e32 v120, 16, v163
	v_add_u32_e32 v120, s25, v120
	s_and_b64 vcc, exec, s[6:7]
	v_ashrrev_i32_e32 v121, 31, v120
	v_cvt_pk_bf16_f32 v150, v128, v129
	v_cvt_pk_bf16_f32 v151, v122, v123
	global_store_dwordx4 v[146:147], v[148:151], off offset:256 nt
	s_cbranch_vccnz .LBB0_399
	v_lshlrev_b64 v[122:123], 6, v[120:121]
	v_lshl_add_u64 v[124:125], v[168:169], 0, v[122:123]
	global_load_dwordx4 v[128:131], v[124:125], off
	global_load_dwordx4 v[140:143], v[124:125], off offset:16
	v_lshl_add_u64 v[122:123], v[166:167], 0, v[122:123]
	global_load_dwordx4 v[124:127], v[122:123], off offset:16
	global_load_dwordx4 v[132:135], v[122:123], off
	s_waitcnt vmcnt(3)
	v_xor_b32_e32 v122, 0x80000000, v128
	v_xor_b32_e32 v123, 0x80000000, v129
	v_xor_b32_e32 v136, 0x80000000, v130
	v_xor_b32_e32 v137, 0x80000000, v131
	s_waitcnt vmcnt(2)
	v_xor_b32_e32 v146, 0x80000000, v140
	v_xor_b32_e32 v147, 0x80000000, v141
	v_xor_b32_e32 v148, 0x80000000, v142
	v_xor_b32_e32 v149, 0x80000000, v143
	v_cndmask_b32_e64 v139, v131, v137, s[2:3]
	v_cndmask_b32_e64 v138, v130, v136, s[2:3]
	v_cndmask_b32_e64 v137, v129, v123, s[2:3]
	v_cndmask_b32_e64 v136, v128, v122, s[2:3]
	v_cndmask_b32_e64 v143, v143, v149, s[2:3]
	v_cndmask_b32_e64 v142, v142, v148, s[2:3]
	v_cndmask_b32_e64 v141, v141, v147, s[2:3]
	v_cndmask_b32_e64 v140, v140, v146, s[2:3]

.LBB0_401:
	v_cvt_pk_bf16_f32 v108, v108, v109
	v_cvt_pk_bf16_f32 v109, v104, v105
	v_add_u32_e32 v104, s57, v214
	v_cvt_pk_bf16_f32 v110, v110, v111
	v_cvt_pk_bf16_f32 v111, v106, v107
	ds_read_b128 v[104:107], v104 offset:16
	s_and_b64 vcc, exec, s[6:7]
	s_waitcnt lgkmcnt(0)
	v_mov_b32_e32 v122, v105
	v_mov_b32_e32 v123, v106
	v_mov_b32_e32 v105, v107
	v_pk_add_f32 v[104:105], v[122:123], v[104:105]
	s_nop 0
	v_add_f32_e32 v104, v104, v105
	v_fmamk_f32 v104, v104, 0x3c000000, v202
	v_rsq_f32_e32 v106, v104
	v_lshlrev_b64 v[104:105], 12, v[120:121]
	v_lshl_add_u64 v[104:105], v[144:145], 0, v[104:105]
	global_store_dwordx4 v[104:105], v[108:111], off nt
	s_nop 1
	v_mul_f32_e32 v108, v203, v106
	v_pk_mul_f32 v[106:107], v[96:97], v[108:109] op_sel_hi:[1,0]
	v_pk_mul_f32 v[96:97], v[98:99], v[108:109] op_sel_hi:[1,0]
	v_pk_mul_f32 v[100:101], v[100:101], v[108:109] op_sel_hi:[1,0]
	v_pk_mul_f32 v[98:99], v[102:103], v[108:109] op_sel_hi:[1,0]
	v_pk_mul_f32 v[96:97], v[118:119], v[96:97]
	v_pk_mul_f32 v[106:107], v[116:117], v[106:107]
	v_pk_mul_f32 v[98:99], v[114:115], v[98:99]
	v_pk_mul_f32 v[100:101], v[112:113], v[100:101]
	s_cbranch_vccnz .LBB0_403
	v_mov_b32_e32 v102, v106
	v_mov_b32_e32 v108, v106
	v_mov_b32_e32 v110, v100
	v_mov_b32_e32 v111, v100
	v_permlane32_swap_b32_e32 v102, v108
	s_nop 0
	v_permlane32_swap_b32_e32 v110, v111
	v_mov_b32_e32 v103, v107
	v_mov_b32_e32 v109, v107
	v_mov_b32_e32 v120, v101
	v_mov_b32_e32 v121, v101
	v_cndmask_b32_e64 v102, v102, v108, s[2:3]
	v_cndmask_b32_e64 v108, v110, v111, s[2:3]
	v_mov_b32_e32 v110, v96
	v_mov_b32_e32 v111, v96
	v_permlane32_swap_b32_e32 v103, v109
	v_permlane32_swap_b32_e32 v120, v121
	v_permlane32_swap_b32_e32 v110, v111
	v_cndmask_b32_e64 v103, v103, v109, s[2:3]
	v_cndmask_b32_e64 v109, v120, v121, s[2:3]
	v_cndmask_b32_e64 v110, v110, v111, s[2:3]
	v_mov_b32_e32 v111, v98
	v_mov_b32_e32 v120, v98
	s_nop 1
	v_permlane32_swap_b32_e32 v111, v120
	v_cndmask_b32_e64 v111, v111, v120, s[2:3]
	v_mul_f32_e32 v120, v142, v111
	v_mov_b32_e32 v111, v97
	v_mov_b32_e32 v121, v97
	s_nop 1
	v_permlane32_swap_b32_e32 v111, v121
	v_cndmask_b32_e64 v123, v111, v121, s[2:3]
	v_mov_b32_e32 v111, v99
	v_mov_b32_e32 v121, v99
	s_waitcnt vmcnt(1)
	v_pk_mul_f32 v[106:107], v[132:133], v[106:107]
	v_permlane32_swap_b32_e32 v111, v121
	v_cndmask_b32_e64 v129, v111, v121, s[2:3]
	v_mov_b32_e32 v130, v135
	v_mov_b32_e32 v131, v139
	v_mov_b32_e32 v122, v97
	v_pk_fma_f32 v[106:107], v[136:137], v[102:103], v[106:107]
	v_mov_b32_e32 v102, v127
	v_mov_b32_e32 v103, v143
	v_mov_b32_e32 v128, v99
	v_pk_mul_f32 v[122:123], v[130:131], v[122:123]
	v_pk_mul_f32 v[102:103], v[102:103], v[128:129]
	v_pk_mul_f32 v[100:101], v[124:125], v[100:101]
	v_mul_f32_e32 v96, v134, v96
	v_mul_f32_e32 v110, v138, v110
	v_mul_f32_e32 v98, v126, v98
	v_mov_b32_e32 v97, v122
	v_mov_b32_e32 v111, v123
	v_mov_b32_e32 v99, v102
	v_mov_b32_e32 v121, v103
	v_pk_add_f32 v[96:97], v[96:97], v[110:111]
	v_pk_fma_f32 v[100:101], v[140:141], v[108:109], v[100:101]
	v_pk_add_f32 v[98:99], v[98:99], v[120:121]
.LBB0_403:
	v_cvt_pk_bf16_f32 v106, v106, v107
	v_cvt_pk_bf16_f32 v107, v96, v97
	v_or_b32_e32 v96, 32, v163
	v_add_u32_e32 v96, s25, v96
	s_and_b64 vcc, exec, s[6:7]
	v_ashrrev_i32_e32 v97, 31, v96
	v_cvt_pk_bf16_f32 v108, v100, v101
	v_cvt_pk_bf16_f32 v109, v98, v99
	global_store_dwordx4 v[104:105], v[106:109], off offset:256 nt
	s_cbranch_vccnz .LBB0_405
	s_nop 0
	v_lshlrev_b64 v[106:107], 6, v[96:97]
	v_lshl_add_u64 v[102:103], v[168:169], 0, v[106:107]
	global_load_dwordx4 v[98:101], v[102:103], off
	s_nop 0
	global_load_dwordx4 v[102:105], v[102:103], off offset:16
	v_lshl_add_u64 v[106:107], v[166:167], 0, v[106:107]
	global_load_dwordx4 v[124:127], v[106:107], off offset:16
	global_load_dwordx4 v[132:135], v[106:107], off
	s_waitcnt vmcnt(3)
	v_xor_b32_e32 v106, 0x80000000, v98
	v_xor_b32_e32 v107, 0x80000000, v99
	v_xor_b32_e32 v108, 0x80000000, v100
	v_xor_b32_e32 v109, 0x80000000, v101
	s_waitcnt vmcnt(2)
	v_xor_b32_e32 v110, 0x80000000, v102
	v_xor_b32_e32 v111, 0x80000000, v103
	v_xor_b32_e32 v120, 0x80000000, v104
	v_xor_b32_e32 v121, 0x80000000, v105
	v_cndmask_b32_e64 v139, v101, v109, s[2:3]
	v_cndmask_b32_e64 v138, v100, v108, s[2:3]
	v_cndmask_b32_e64 v137, v99, v107, s[2:3]
	v_cndmask_b32_e64 v136, v98, v106, s[2:3]
	v_cndmask_b32_e64 v143, v105, v121, s[2:3]
	v_cndmask_b32_e64 v142, v104, v120, s[2:3]
	v_cndmask_b32_e64 v141, v103, v111, s[2:3]
	v_cndmask_b32_e64 v140, v102, v110, s[2:3]

.LBB0_407:
	v_cvt_pk_bf16_f32 v92, v92, v93
	v_cvt_pk_bf16_f32 v93, v88, v89
	v_add_u32_e32 v88, s57, v215
	v_cvt_pk_bf16_f32 v94, v94, v95
	v_cvt_pk_bf16_f32 v95, v90, v91
	ds_read_b128 v[88:91], v88 offset:16
	s_and_b64 vcc, exec, s[6:7]
	s_waitcnt lgkmcnt(0)
	v_mov_b32_e32 v98, v89
	v_mov_b32_e32 v99, v90
	v_mov_b32_e32 v89, v91
	v_pk_add_f32 v[88:89], v[98:99], v[88:89]
	s_nop 0
	v_add_f32_e32 v88, v88, v89
	v_fmamk_f32 v88, v88, 0x3c000000, v202
	v_rsq_f32_e32 v90, v88
	v_lshlrev_b64 v[88:89], 12, v[96:97]
	v_lshl_add_u64 v[88:89], v[144:145], 0, v[88:89]
	global_store_dwordx4 v[88:89], v[92:95], off nt
	s_nop 1
	v_mul_f32_e32 v92, v203, v90
	v_pk_mul_f32 v[90:91], v[80:81], v[92:93] op_sel_hi:[1,0]
	v_pk_mul_f32 v[80:81], v[82:83], v[92:93] op_sel_hi:[1,0]
	v_pk_mul_f32 v[84:85], v[84:85], v[92:93] op_sel_hi:[1,0]
	v_pk_mul_f32 v[82:83], v[86:87], v[92:93] op_sel_hi:[1,0]
	v_pk_mul_f32 v[80:81], v[118:119], v[80:81]
	v_pk_mul_f32 v[90:91], v[116:117], v[90:91]
	v_pk_mul_f32 v[82:83], v[114:115], v[82:83]
	v_pk_mul_f32 v[84:85], v[112:113], v[84:85]
	s_cbranch_vccnz .LBB0_409
	v_mov_b32_e32 v86, v90
	v_mov_b32_e32 v92, v90
	v_mov_b32_e32 v94, v84
	v_mov_b32_e32 v95, v84
	v_permlane32_swap_b32_e32 v86, v92
	s_nop 0
	v_permlane32_swap_b32_e32 v94, v95
	v_mov_b32_e32 v87, v91
	v_mov_b32_e32 v93, v91
	v_mov_b32_e32 v96, v85
	v_mov_b32_e32 v97, v85
	v_cndmask_b32_e64 v86, v86, v92, s[2:3]
	v_cndmask_b32_e64 v92, v94, v95, s[2:3]
	v_mov_b32_e32 v94, v80
	v_mov_b32_e32 v95, v80
	v_permlane32_swap_b32_e32 v87, v93
	v_permlane32_swap_b32_e32 v96, v97
	v_permlane32_swap_b32_e32 v94, v95
	v_cndmask_b32_e64 v87, v87, v93, s[2:3]
	v_cndmask_b32_e64 v93, v96, v97, s[2:3]
	v_cndmask_b32_e64 v94, v94, v95, s[2:3]
	v_mov_b32_e32 v95, v82
	v_mov_b32_e32 v96, v82
	s_nop 1
	v_permlane32_swap_b32_e32 v95, v96
	v_cndmask_b32_e64 v95, v95, v96, s[2:3]
	v_mul_f32_e32 v96, v142, v95
	v_mov_b32_e32 v95, v81
	v_mov_b32_e32 v97, v81
	s_nop 1
	v_permlane32_swap_b32_e32 v95, v97
	v_cndmask_b32_e64 v99, v95, v97, s[2:3]
	v_mov_b32_e32 v95, v83
	v_mov_b32_e32 v97, v83
	s_waitcnt vmcnt(1)
	v_pk_mul_f32 v[90:91], v[132:133], v[90:91]
	v_permlane32_swap_b32_e32 v95, v97
	v_cndmask_b32_e64 v101, v95, v97, s[2:3]
	v_mov_b32_e32 v102, v135
	v_mov_b32_e32 v103, v139
	v_mov_b32_e32 v98, v81
	v_pk_fma_f32 v[90:91], v[136:137], v[86:87], v[90:91]
	v_mov_b32_e32 v86, v127
	v_mov_b32_e32 v87, v143
	v_mov_b32_e32 v100, v83
	v_pk_mul_f32 v[98:99], v[102:103], v[98:99]
	v_pk_mul_f32 v[86:87], v[86:87], v[100:101]
	v_pk_mul_f32 v[84:85], v[124:125], v[84:85]
	v_mul_f32_e32 v80, v134, v80
	v_mul_f32_e32 v94, v138, v94
	v_mul_f32_e32 v82, v126, v82
	v_mov_b32_e32 v81, v98
	v_mov_b32_e32 v95, v99
	v_mov_b32_e32 v83, v86
	v_mov_b32_e32 v97, v87
	v_pk_add_f32 v[80:81], v[80:81], v[94:95]
	v_pk_fma_f32 v[84:85], v[140:141], v[92:93], v[84:85]
	v_pk_add_f32 v[82:83], v[82:83], v[96:97]
.LBB0_409:
	v_cvt_pk_bf16_f32 v90, v90, v91
	v_cvt_pk_bf16_f32 v91, v80, v81
	v_or_b32_e32 v80, 48, v163
	v_add_u32_e32 v80, s25, v80
	s_and_b64 vcc, exec, s[6:7]
	v_ashrrev_i32_e32 v81, 31, v80
	v_cvt_pk_bf16_f32 v92, v84, v85
	v_cvt_pk_bf16_f32 v93, v82, v83
	global_store_dwordx4 v[88:89], v[90:93], off offset:256 nt
	s_cbranch_vccnz .LBB0_411
	s_nop 0
	v_lshlrev_b64 v[90:91], 6, v[80:81]
	v_lshl_add_u64 v[86:87], v[168:169], 0, v[90:91]
	global_load_dwordx4 v[82:85], v[86:87], off
	s_nop 0
	global_load_dwordx4 v[86:89], v[86:87], off offset:16
	v_lshl_add_u64 v[90:91], v[166:167], 0, v[90:91]
	global_load_dwordx4 v[124:127], v[90:91], off offset:16
	global_load_dwordx4 v[132:135], v[90:91], off
	s_waitcnt vmcnt(3)
	v_xor_b32_e32 v90, 0x80000000, v82
	v_xor_b32_e32 v91, 0x80000000, v83
	v_xor_b32_e32 v92, 0x80000000, v84
	v_xor_b32_e32 v93, 0x80000000, v85
	s_waitcnt vmcnt(2)
	v_xor_b32_e32 v94, 0x80000000, v86
	v_xor_b32_e32 v95, 0x80000000, v87
	v_xor_b32_e32 v96, 0x80000000, v88
	v_xor_b32_e32 v97, 0x80000000, v89
	v_cndmask_b32_e64 v139, v85, v93, s[2:3]
	v_cndmask_b32_e64 v138, v84, v92, s[2:3]
	v_cndmask_b32_e64 v137, v83, v91, s[2:3]
	v_cndmask_b32_e64 v136, v82, v90, s[2:3]
	v_cndmask_b32_e64 v143, v89, v97, s[2:3]
	v_cndmask_b32_e64 v142, v88, v96, s[2:3]
	v_cndmask_b32_e64 v141, v87, v95, s[2:3]
	v_cndmask_b32_e64 v140, v86, v94, s[2:3]

.LBB0_413:
	v_cvt_pk_bf16_f32 v76, v76, v77
	v_cvt_pk_bf16_f32 v77, v72, v73
	v_add_u32_e32 v72, s57, v185
	v_cvt_pk_bf16_f32 v78, v78, v79
	v_cvt_pk_bf16_f32 v79, v74, v75
	ds_read_b128 v[72:75], v72 offset:16
	s_and_b64 vcc, exec, s[6:7]
	s_waitcnt lgkmcnt(0)
	v_mov_b32_e32 v82, v73
	v_mov_b32_e32 v83, v74
	v_mov_b32_e32 v73, v75
	v_pk_add_f32 v[72:73], v[82:83], v[72:73]
	s_nop 0
	v_add_f32_e32 v72, v72, v73
	v_fmamk_f32 v72, v72, 0x3c000000, v202
	v_rsq_f32_e32 v74, v72
	v_lshlrev_b64 v[72:73], 12, v[80:81]
	v_lshl_add_u64 v[72:73], v[144:145], 0, v[72:73]
	global_store_dwordx4 v[72:73], v[76:79], off nt
	s_nop 1
	v_mul_f32_e32 v76, v203, v74
	v_pk_mul_f32 v[74:75], v[64:65], v[76:77] op_sel_hi:[1,0]
	v_pk_mul_f32 v[64:65], v[66:67], v[76:77] op_sel_hi:[1,0]
	v_pk_mul_f32 v[68:69], v[68:69], v[76:77] op_sel_hi:[1,0]
	v_pk_mul_f32 v[66:67], v[70:71], v[76:77] op_sel_hi:[1,0]
	v_pk_mul_f32 v[64:65], v[118:119], v[64:65]
	v_pk_mul_f32 v[74:75], v[116:117], v[74:75]
	v_pk_mul_f32 v[66:67], v[114:115], v[66:67]
	v_pk_mul_f32 v[68:69], v[112:113], v[68:69]
	s_cbranch_vccnz .LBB0_415
	v_mov_b32_e32 v70, v74
	v_mov_b32_e32 v76, v74
	v_mov_b32_e32 v78, v68
	v_mov_b32_e32 v79, v68
	v_permlane32_swap_b32_e32 v70, v76
	s_nop 0
	v_permlane32_swap_b32_e32 v78, v79
	v_mov_b32_e32 v71, v75
	v_mov_b32_e32 v77, v75
	v_mov_b32_e32 v80, v69
	v_mov_b32_e32 v81, v69
	v_cndmask_b32_e64 v70, v70, v76, s[2:3]
	v_cndmask_b32_e64 v76, v78, v79, s[2:3]
	v_mov_b32_e32 v78, v64
	v_mov_b32_e32 v79, v64
	v_permlane32_swap_b32_e32 v71, v77
	v_permlane32_swap_b32_e32 v80, v81
	v_permlane32_swap_b32_e32 v78, v79
	v_cndmask_b32_e64 v71, v71, v77, s[2:3]
	v_cndmask_b32_e64 v77, v80, v81, s[2:3]
	v_cndmask_b32_e64 v78, v78, v79, s[2:3]
	v_mov_b32_e32 v79, v66
	v_mov_b32_e32 v80, v66
	s_nop 1
	v_permlane32_swap_b32_e32 v79, v80
	v_cndmask_b32_e64 v79, v79, v80, s[2:3]
	v_mul_f32_e32 v80, v142, v79
	v_mov_b32_e32 v79, v65
	v_mov_b32_e32 v81, v65
	s_nop 1
	v_permlane32_swap_b32_e32 v79, v81
	v_cndmask_b32_e64 v83, v79, v81, s[2:3]
	v_mov_b32_e32 v79, v67
	v_mov_b32_e32 v81, v67
	s_waitcnt vmcnt(1)
	v_pk_mul_f32 v[74:75], v[132:133], v[74:75]
	v_permlane32_swap_b32_e32 v79, v81
	v_cndmask_b32_e64 v85, v79, v81, s[2:3]
	v_mov_b32_e32 v86, v135
	v_mov_b32_e32 v87, v139
	v_mov_b32_e32 v82, v65
	v_pk_fma_f32 v[74:75], v[136:137], v[70:71], v[74:75]
	v_mov_b32_e32 v70, v127
	v_mov_b32_e32 v71, v143
	v_mov_b32_e32 v84, v67
	v_pk_mul_f32 v[82:83], v[86:87], v[82:83]
	v_pk_mul_f32 v[70:71], v[70:71], v[84:85]
	v_pk_mul_f32 v[68:69], v[124:125], v[68:69]
	v_mul_f32_e32 v64, v134, v64
	v_mul_f32_e32 v78, v138, v78
	v_mul_f32_e32 v66, v126, v66
	v_mov_b32_e32 v65, v82
	v_mov_b32_e32 v79, v83
	v_mov_b32_e32 v67, v70
	v_mov_b32_e32 v81, v71
	v_pk_add_f32 v[64:65], v[64:65], v[78:79]
	v_pk_fma_f32 v[68:69], v[140:141], v[76:77], v[68:69]
	v_pk_add_f32 v[66:67], v[66:67], v[80:81]
.LBB0_415:
	v_cvt_pk_bf16_f32 v74, v74, v75
	v_cvt_pk_bf16_f32 v75, v64, v65
	v_add_u32_e32 v64, s25, v181
	s_and_b64 vcc, exec, s[6:7]
	v_ashrrev_i32_e32 v65, 31, v64
	v_cvt_pk_bf16_f32 v76, v68, v69
	v_cvt_pk_bf16_f32 v77, v66, v67
	global_store_dwordx4 v[72:73], v[74:77], off offset:256 nt
	s_cbranch_vccnz .LBB0_417
	s_nop 0
	v_lshlrev_b64 v[74:75], 6, v[64:65]
	v_lshl_add_u64 v[70:71], v[168:169], 0, v[74:75]
	global_load_dwordx4 v[66:69], v[70:71], off
	s_nop 0
	global_load_dwordx4 v[70:73], v[70:71], off offset:16
	v_lshl_add_u64 v[74:75], v[166:167], 0, v[74:75]
	global_load_dwordx4 v[124:127], v[74:75], off offset:16
	global_load_dwordx4 v[132:135], v[74:75], off
	s_waitcnt vmcnt(3)
	v_xor_b32_e32 v74, 0x80000000, v66
	v_xor_b32_e32 v75, 0x80000000, v67
	v_xor_b32_e32 v76, 0x80000000, v68
	v_xor_b32_e32 v77, 0x80000000, v69
	s_waitcnt vmcnt(2)
	v_xor_b32_e32 v78, 0x80000000, v70
	v_xor_b32_e32 v79, 0x80000000, v71
	v_xor_b32_e32 v80, 0x80000000, v72
	v_xor_b32_e32 v81, 0x80000000, v73
	v_cndmask_b32_e64 v139, v69, v77, s[2:3]
	v_cndmask_b32_e64 v138, v68, v76, s[2:3]
	v_cndmask_b32_e64 v137, v67, v75, s[2:3]
	v_cndmask_b32_e64 v136, v66, v74, s[2:3]
	v_cndmask_b32_e64 v143, v73, v81, s[2:3]
	v_cndmask_b32_e64 v142, v72, v80, s[2:3]
	v_cndmask_b32_e64 v141, v71, v79, s[2:3]
	v_cndmask_b32_e64 v140, v70, v78, s[2:3]

.LBB0_419:
	v_cvt_pk_bf16_f32 v60, v60, v61
	v_cvt_pk_bf16_f32 v61, v56, v57
	v_add_u32_e32 v56, s57, v190
	v_cvt_pk_bf16_f32 v62, v62, v63
	v_cvt_pk_bf16_f32 v63, v58, v59
	ds_read_b128 v[56:59], v56 offset:16
	s_and_b64 vcc, exec, s[6:7]
	s_waitcnt lgkmcnt(0)
	v_mov_b32_e32 v66, v57
	v_mov_b32_e32 v67, v58
	v_mov_b32_e32 v57, v59
	v_pk_add_f32 v[56:57], v[66:67], v[56:57]
	s_nop 0
	v_add_f32_e32 v56, v56, v57
	v_fmamk_f32 v56, v56, 0x3c000000, v202
	v_rsq_f32_e32 v58, v56
	v_lshlrev_b64 v[56:57], 12, v[64:65]
	v_lshl_add_u64 v[56:57], v[144:145], 0, v[56:57]
	global_store_dwordx4 v[56:57], v[60:63], off nt
	s_nop 1
	v_mul_f32_e32 v60, v203, v58
	v_pk_mul_f32 v[58:59], v[48:49], v[60:61] op_sel_hi:[1,0]
	v_pk_mul_f32 v[48:49], v[50:51], v[60:61] op_sel_hi:[1,0]
	v_pk_mul_f32 v[52:53], v[52:53], v[60:61] op_sel_hi:[1,0]
	v_pk_mul_f32 v[50:51], v[54:55], v[60:61] op_sel_hi:[1,0]
	v_pk_mul_f32 v[48:49], v[118:119], v[48:49]
	v_pk_mul_f32 v[58:59], v[116:117], v[58:59]
	v_pk_mul_f32 v[50:51], v[114:115], v[50:51]
	v_pk_mul_f32 v[52:53], v[112:113], v[52:53]
	s_cbranch_vccnz .LBB0_421
	v_mov_b32_e32 v54, v58
	v_mov_b32_e32 v60, v58
	v_mov_b32_e32 v62, v52
	v_mov_b32_e32 v63, v52
	v_permlane32_swap_b32_e32 v54, v60
	s_nop 0
	v_permlane32_swap_b32_e32 v62, v63
	v_mov_b32_e32 v55, v59
	v_mov_b32_e32 v61, v59
	v_mov_b32_e32 v64, v53
	v_mov_b32_e32 v65, v53
	v_cndmask_b32_e64 v54, v54, v60, s[2:3]
	v_cndmask_b32_e64 v60, v62, v63, s[2:3]
	v_mov_b32_e32 v62, v48
	v_mov_b32_e32 v63, v48
	v_permlane32_swap_b32_e32 v55, v61
	v_permlane32_swap_b32_e32 v64, v65
	v_permlane32_swap_b32_e32 v62, v63
	v_cndmask_b32_e64 v55, v55, v61, s[2:3]
	v_cndmask_b32_e64 v61, v64, v65, s[2:3]
	v_cndmask_b32_e64 v62, v62, v63, s[2:3]
	v_mov_b32_e32 v63, v50
	v_mov_b32_e32 v64, v50
	s_nop 1
	v_permlane32_swap_b32_e32 v63, v64
	v_cndmask_b32_e64 v63, v63, v64, s[2:3]
	v_mul_f32_e32 v64, v142, v63
	v_mov_b32_e32 v63, v49
	v_mov_b32_e32 v65, v49
	s_nop 1
	v_permlane32_swap_b32_e32 v63, v65
	v_cndmask_b32_e64 v67, v63, v65, s[2:3]
	v_mov_b32_e32 v63, v51
	v_mov_b32_e32 v65, v51
	s_waitcnt vmcnt(1)
	v_pk_mul_f32 v[58:59], v[132:133], v[58:59]
	v_permlane32_swap_b32_e32 v63, v65
	v_cndmask_b32_e64 v69, v63, v65, s[2:3]
	v_mov_b32_e32 v70, v135
	v_mov_b32_e32 v71, v139
	v_mov_b32_e32 v66, v49
	v_pk_fma_f32 v[58:59], v[136:137], v[54:55], v[58:59]
	v_mov_b32_e32 v54, v127
	v_mov_b32_e32 v55, v143
	v_mov_b32_e32 v68, v51
	v_pk_mul_f32 v[66:67], v[70:71], v[66:67]
	v_pk_mul_f32 v[54:55], v[54:55], v[68:69]
	v_pk_mul_f32 v[52:53], v[124:125], v[52:53]
	v_mul_f32_e32 v48, v134, v48
	v_mul_f32_e32 v62, v138, v62
	v_mul_f32_e32 v50, v126, v50
	v_mov_b32_e32 v49, v66
	v_mov_b32_e32 v63, v67
	v_mov_b32_e32 v51, v54
	v_mov_b32_e32 v65, v55
	v_pk_add_f32 v[48:49], v[48:49], v[62:63]
	v_pk_fma_f32 v[52:53], v[140:141], v[60:61], v[52:53]
	v_pk_add_f32 v[50:51], v[50:51], v[64:65]
.LBB0_421:
	v_cvt_pk_bf16_f32 v58, v58, v59
	v_cvt_pk_bf16_f32 v59, v48, v49
	v_add_u32_e32 v48, s25, v182
	s_and_b64 vcc, exec, s[6:7]
	v_ashrrev_i32_e32 v49, 31, v48
	v_cvt_pk_bf16_f32 v60, v52, v53
	v_cvt_pk_bf16_f32 v61, v50, v51
	global_store_dwordx4 v[56:57], v[58:61], off offset:256 nt
	s_cbranch_vccnz .LBB0_423
	s_nop 0
	v_lshlrev_b64 v[58:59], 6, v[48:49]
	v_lshl_add_u64 v[54:55], v[168:169], 0, v[58:59]
	global_load_dwordx4 v[50:53], v[54:55], off
	s_nop 0
	global_load_dwordx4 v[54:57], v[54:55], off offset:16
	v_lshl_add_u64 v[58:59], v[166:167], 0, v[58:59]
	global_load_dwordx4 v[124:127], v[58:59], off offset:16
	global_load_dwordx4 v[132:135], v[58:59], off
	s_waitcnt vmcnt(3)
	v_xor_b32_e32 v58, 0x80000000, v50
	v_xor_b32_e32 v59, 0x80000000, v51
	v_xor_b32_e32 v60, 0x80000000, v52
	v_xor_b32_e32 v61, 0x80000000, v53
	s_waitcnt vmcnt(2)
	v_xor_b32_e32 v62, 0x80000000, v54
	v_xor_b32_e32 v63, 0x80000000, v55
	v_xor_b32_e32 v64, 0x80000000, v56
	v_xor_b32_e32 v65, 0x80000000, v57
	v_cndmask_b32_e64 v139, v53, v61, s[2:3]
	v_cndmask_b32_e64 v138, v52, v60, s[2:3]
	v_cndmask_b32_e64 v137, v51, v59, s[2:3]
	v_cndmask_b32_e64 v136, v50, v58, s[2:3]
	v_cndmask_b32_e64 v143, v57, v65, s[2:3]
	v_cndmask_b32_e64 v142, v56, v64, s[2:3]
	v_cndmask_b32_e64 v141, v55, v63, s[2:3]
	v_cndmask_b32_e64 v140, v54, v62, s[2:3]

.LBB0_425:
	v_cvt_pk_bf16_f32 v44, v44, v45
	v_cvt_pk_bf16_f32 v45, v40, v41
	v_add_u32_e32 v40, s57, v191
	v_cvt_pk_bf16_f32 v46, v46, v47
	v_cvt_pk_bf16_f32 v47, v42, v43
	ds_read_b128 v[40:43], v40 offset:16
	s_and_b64 vcc, exec, s[6:7]
	s_waitcnt lgkmcnt(0)
	v_mov_b32_e32 v50, v41
	v_mov_b32_e32 v51, v42
	v_mov_b32_e32 v41, v43
	v_pk_add_f32 v[40:41], v[50:51], v[40:41]
	s_nop 0
	v_add_f32_e32 v40, v40, v41
	v_fmamk_f32 v40, v40, 0x3c000000, v202
	v_rsq_f32_e32 v42, v40
	v_lshlrev_b64 v[40:41], 12, v[48:49]
	v_lshl_add_u64 v[40:41], v[144:145], 0, v[40:41]
	global_store_dwordx4 v[40:41], v[44:47], off nt
	s_nop 1
	v_mul_f32_e32 v44, v203, v42
	v_pk_mul_f32 v[42:43], v[32:33], v[44:45] op_sel_hi:[1,0]
	v_pk_mul_f32 v[32:33], v[34:35], v[44:45] op_sel_hi:[1,0]
	v_pk_mul_f32 v[36:37], v[36:37], v[44:45] op_sel_hi:[1,0]
	v_pk_mul_f32 v[34:35], v[38:39], v[44:45] op_sel_hi:[1,0]
	v_pk_mul_f32 v[32:33], v[118:119], v[32:33]
	v_pk_mul_f32 v[42:43], v[116:117], v[42:43]
	v_pk_mul_f32 v[34:35], v[114:115], v[34:35]
	v_pk_mul_f32 v[36:37], v[112:113], v[36:37]
	s_cbranch_vccnz .LBB0_427
	v_mov_b32_e32 v38, v42
	v_mov_b32_e32 v44, v42
	v_mov_b32_e32 v46, v36
	v_mov_b32_e32 v47, v36
	v_permlane32_swap_b32_e32 v38, v44
	s_nop 0
	v_permlane32_swap_b32_e32 v46, v47
	v_mov_b32_e32 v39, v43
	v_mov_b32_e32 v45, v43
	v_mov_b32_e32 v48, v37
	v_mov_b32_e32 v49, v37
	v_cndmask_b32_e64 v38, v38, v44, s[2:3]
	v_cndmask_b32_e64 v44, v46, v47, s[2:3]
	v_mov_b32_e32 v46, v32
	v_mov_b32_e32 v47, v32
	v_permlane32_swap_b32_e32 v39, v45
	v_permlane32_swap_b32_e32 v48, v49
	v_permlane32_swap_b32_e32 v46, v47
	v_cndmask_b32_e64 v39, v39, v45, s[2:3]
	v_cndmask_b32_e64 v45, v48, v49, s[2:3]
	v_cndmask_b32_e64 v46, v46, v47, s[2:3]
	v_mov_b32_e32 v47, v34
	v_mov_b32_e32 v48, v34
	s_nop 1
	v_permlane32_swap_b32_e32 v47, v48
	v_cndmask_b32_e64 v47, v47, v48, s[2:3]
	v_mul_f32_e32 v48, v142, v47
	v_mov_b32_e32 v47, v33
	v_mov_b32_e32 v49, v33
	s_nop 1
	v_permlane32_swap_b32_e32 v47, v49
	v_cndmask_b32_e64 v51, v47, v49, s[2:3]
	v_mov_b32_e32 v47, v35
	v_mov_b32_e32 v49, v35
	s_waitcnt vmcnt(1)
	v_pk_mul_f32 v[42:43], v[132:133], v[42:43]
	v_permlane32_swap_b32_e32 v47, v49
	v_cndmask_b32_e64 v53, v47, v49, s[2:3]
	v_mov_b32_e32 v54, v135
	v_mov_b32_e32 v55, v139
	v_mov_b32_e32 v50, v33
	v_pk_fma_f32 v[42:43], v[136:137], v[38:39], v[42:43]
	v_mov_b32_e32 v38, v127
	v_mov_b32_e32 v39, v143
	v_mov_b32_e32 v52, v35
	v_pk_mul_f32 v[50:51], v[54:55], v[50:51]
	v_pk_mul_f32 v[38:39], v[38:39], v[52:53]
	v_pk_mul_f32 v[36:37], v[124:125], v[36:37]
	v_mul_f32_e32 v32, v134, v32
	v_mul_f32_e32 v46, v138, v46
	v_mul_f32_e32 v34, v126, v34
	v_mov_b32_e32 v33, v50
	v_mov_b32_e32 v47, v51
	v_mov_b32_e32 v35, v38
	v_mov_b32_e32 v49, v39
	v_pk_add_f32 v[32:33], v[32:33], v[46:47]
	v_pk_fma_f32 v[36:37], v[140:141], v[44:45], v[36:37]
	v_pk_add_f32 v[34:35], v[34:35], v[48:49]
.LBB0_427:
	v_cvt_pk_bf16_f32 v42, v42, v43
	v_cvt_pk_bf16_f32 v43, v32, v33
	v_add_u32_e32 v32, s25, v183
	s_and_b64 vcc, exec, s[6:7]
	v_ashrrev_i32_e32 v33, 31, v32
	v_cvt_pk_bf16_f32 v44, v36, v37
	v_cvt_pk_bf16_f32 v45, v34, v35
	global_store_dwordx4 v[40:41], v[42:45], off offset:256 nt
	s_cbranch_vccnz .LBB0_429
	s_nop 0
	v_lshlrev_b64 v[42:43], 6, v[32:33]
	v_lshl_add_u64 v[38:39], v[168:169], 0, v[42:43]
	global_load_dwordx4 v[34:37], v[38:39], off
	s_nop 0
	global_load_dwordx4 v[38:41], v[38:39], off offset:16
	v_lshl_add_u64 v[42:43], v[166:167], 0, v[42:43]
	global_load_dwordx4 v[124:127], v[42:43], off offset:16
	global_load_dwordx4 v[132:135], v[42:43], off
	s_waitcnt vmcnt(3)
	v_xor_b32_e32 v42, 0x80000000, v34
	v_xor_b32_e32 v43, 0x80000000, v35
	v_xor_b32_e32 v44, 0x80000000, v36
	v_xor_b32_e32 v45, 0x80000000, v37
	s_waitcnt vmcnt(2)
	v_xor_b32_e32 v46, 0x80000000, v38
	v_xor_b32_e32 v47, 0x80000000, v39
	v_xor_b32_e32 v48, 0x80000000, v40
	v_xor_b32_e32 v49, 0x80000000, v41
	v_cndmask_b32_e64 v139, v37, v45, s[2:3]
	v_cndmask_b32_e64 v138, v36, v44, s[2:3]
	v_cndmask_b32_e64 v137, v35, v43, s[2:3]
	v_cndmask_b32_e64 v136, v34, v42, s[2:3]
	v_cndmask_b32_e64 v143, v41, v49, s[2:3]
	v_cndmask_b32_e64 v142, v40, v48, s[2:3]
	v_cndmask_b32_e64 v141, v39, v47, s[2:3]
	v_cndmask_b32_e64 v140, v38, v46, s[2:3]

.LBB0_431:
	v_cvt_pk_bf16_f32 v28, v28, v29
	v_cvt_pk_bf16_f32 v29, v24, v25
	v_add_u32_e32 v24, s57, v178
	v_cvt_pk_bf16_f32 v30, v30, v31
	v_cvt_pk_bf16_f32 v31, v26, v27
	ds_read_b128 v[24:27], v24 offset:16
	s_and_b64 vcc, exec, s[6:7]
	s_waitcnt lgkmcnt(0)
	v_mov_b32_e32 v34, v25
	v_mov_b32_e32 v35, v26
	v_mov_b32_e32 v25, v27
	v_pk_add_f32 v[24:25], v[34:35], v[24:25]
	s_nop 0
	v_add_f32_e32 v24, v24, v25
	v_fmamk_f32 v24, v24, 0x3c000000, v202
	v_rsq_f32_e32 v26, v24
	v_lshlrev_b64 v[24:25], 12, v[32:33]
	v_lshl_add_u64 v[24:25], v[144:145], 0, v[24:25]
	global_store_dwordx4 v[24:25], v[28:31], off nt
	s_nop 1
	v_mul_f32_e32 v28, v203, v26
	v_pk_mul_f32 v[26:27], v[16:17], v[28:29] op_sel_hi:[1,0]
	v_pk_mul_f32 v[16:17], v[18:19], v[28:29] op_sel_hi:[1,0]
	v_pk_mul_f32 v[20:21], v[20:21], v[28:29] op_sel_hi:[1,0]
	v_pk_mul_f32 v[18:19], v[22:23], v[28:29] op_sel_hi:[1,0]
	v_pk_mul_f32 v[16:17], v[118:119], v[16:17]
	v_pk_mul_f32 v[26:27], v[116:117], v[26:27]
	v_pk_mul_f32 v[18:19], v[114:115], v[18:19]
	v_pk_mul_f32 v[20:21], v[112:113], v[20:21]
	s_cbranch_vccnz .LBB0_433
	v_mov_b32_e32 v22, v26
	v_mov_b32_e32 v28, v26
	v_mov_b32_e32 v30, v20
	v_mov_b32_e32 v31, v20
	v_permlane32_swap_b32_e32 v22, v28
	s_nop 0
	v_permlane32_swap_b32_e32 v30, v31
	v_mov_b32_e32 v23, v27
	v_mov_b32_e32 v29, v27
	v_mov_b32_e32 v32, v21
	v_mov_b32_e32 v33, v21
	v_cndmask_b32_e64 v22, v22, v28, s[2:3]
	v_cndmask_b32_e64 v28, v30, v31, s[2:3]
	v_mov_b32_e32 v30, v16
	v_mov_b32_e32 v31, v16
	v_permlane32_swap_b32_e32 v23, v29
	v_permlane32_swap_b32_e32 v32, v33
	v_permlane32_swap_b32_e32 v30, v31
	v_cndmask_b32_e64 v23, v23, v29, s[2:3]
	v_cndmask_b32_e64 v29, v32, v33, s[2:3]
	v_cndmask_b32_e64 v30, v30, v31, s[2:3]
	v_mov_b32_e32 v31, v18
	v_mov_b32_e32 v32, v18
	s_nop 1
	v_permlane32_swap_b32_e32 v31, v32
	v_cndmask_b32_e64 v31, v31, v32, s[2:3]
	v_mul_f32_e32 v32, v142, v31
	v_mov_b32_e32 v31, v17
	v_mov_b32_e32 v33, v17
	s_nop 1
	v_permlane32_swap_b32_e32 v31, v33
	v_cndmask_b32_e64 v35, v31, v33, s[2:3]
	v_mov_b32_e32 v31, v19
	v_mov_b32_e32 v33, v19
	s_waitcnt vmcnt(1)
	v_pk_mul_f32 v[26:27], v[132:133], v[26:27]
	v_permlane32_swap_b32_e32 v31, v33
	v_cndmask_b32_e64 v37, v31, v33, s[2:3]
	v_mov_b32_e32 v38, v135
	v_mov_b32_e32 v39, v139
	v_mov_b32_e32 v34, v17
	v_pk_fma_f32 v[26:27], v[136:137], v[22:23], v[26:27]
	v_mov_b32_e32 v22, v127
	v_mov_b32_e32 v23, v143
	v_mov_b32_e32 v36, v19
	v_pk_mul_f32 v[34:35], v[38:39], v[34:35]
	v_pk_mul_f32 v[22:23], v[22:23], v[36:37]
	v_pk_mul_f32 v[20:21], v[124:125], v[20:21]
	v_mul_f32_e32 v16, v134, v16
	v_mul_f32_e32 v30, v138, v30
	v_mul_f32_e32 v18, v126, v18
	v_mov_b32_e32 v17, v34
	v_mov_b32_e32 v31, v35
	v_mov_b32_e32 v19, v22
	v_mov_b32_e32 v33, v23
	v_pk_add_f32 v[16:17], v[16:17], v[30:31]
	v_pk_fma_f32 v[20:21], v[140:141], v[28:29], v[20:21]
	v_pk_add_f32 v[18:19], v[18:19], v[32:33]
.LBB0_433:
	v_cvt_pk_bf16_f32 v26, v26, v27
	v_cvt_pk_bf16_f32 v27, v16, v17
	v_add_u32_e32 v16, s25, v184
	s_and_b64 vcc, exec, s[6:7]
	v_ashrrev_i32_e32 v17, 31, v16
	v_cvt_pk_bf16_f32 v28, v20, v21
	v_cvt_pk_bf16_f32 v29, v18, v19
	global_store_dwordx4 v[24:25], v[26:29], off offset:256 nt
	s_cbranch_vccnz .LBB0_435
	s_nop 0
	v_lshlrev_b64 v[26:27], 6, v[16:17]
	v_lshl_add_u64 v[22:23], v[168:169], 0, v[26:27]
	global_load_dwordx4 v[18:21], v[22:23], off
	s_nop 0
	global_load_dwordx4 v[22:25], v[22:23], off offset:16
	v_lshl_add_u64 v[26:27], v[166:167], 0, v[26:27]
	global_load_dwordx4 v[124:127], v[26:27], off offset:16
	global_load_dwordx4 v[132:135], v[26:27], off
	s_waitcnt vmcnt(3)
	v_xor_b32_e32 v26, 0x80000000, v18
	v_xor_b32_e32 v27, 0x80000000, v19
	v_xor_b32_e32 v28, 0x80000000, v20
	v_xor_b32_e32 v29, 0x80000000, v21
	s_waitcnt vmcnt(2)
	v_xor_b32_e32 v30, 0x80000000, v22
	v_xor_b32_e32 v31, 0x80000000, v23
	v_xor_b32_e32 v32, 0x80000000, v24
	v_xor_b32_e32 v33, 0x80000000, v25
	v_cndmask_b32_e64 v139, v21, v29, s[2:3]
	v_cndmask_b32_e64 v138, v20, v28, s[2:3]
	v_cndmask_b32_e64 v137, v19, v27, s[2:3]
	v_cndmask_b32_e64 v136, v18, v26, s[2:3]
	v_cndmask_b32_e64 v143, v25, v33, s[2:3]
	v_cndmask_b32_e64 v142, v24, v32, s[2:3]
	v_cndmask_b32_e64 v141, v23, v31, s[2:3]
	v_cndmask_b32_e64 v140, v22, v30, s[2:3]

.LBB0_437:
	v_cvt_pk_bf16_f32 v12, v12, v13
	v_cvt_pk_bf16_f32 v13, v8, v9
	v_add_u32_e32 v8, s57, v180
	v_cvt_pk_bf16_f32 v14, v14, v15
	v_cvt_pk_bf16_f32 v15, v10, v11
	ds_read_b128 v[8:11], v8 offset:16
	s_and_b64 vcc, exec, s[6:7]
	s_waitcnt lgkmcnt(0)
	v_mov_b32_e32 v18, v9
	v_mov_b32_e32 v19, v10
	v_mov_b32_e32 v9, v11
	v_pk_add_f32 v[8:9], v[18:19], v[8:9]
	s_nop 0
	v_add_f32_e32 v8, v8, v9
	v_fmamk_f32 v8, v8, 0x3c000000, v202
	v_rsq_f32_e32 v10, v8
	v_lshlrev_b64 v[8:9], 12, v[16:17]
	v_lshl_add_u64 v[174:175], v[144:145], 0, v[8:9]
	global_store_dwordx4 v[174:175], v[12:15], off nt
	v_mul_f32_e32 v8, v203, v10
	v_pk_mul_f32 v[10:11], v[4:5], v[8:9] op_sel_hi:[1,0]
	v_pk_mul_f32 v[4:5], v[6:7], v[8:9] op_sel_hi:[1,0]
	v_pk_mul_f32 v[6:7], v[116:117], v[10:11]
	v_pk_mul_f32 v[10:11], v[0:1], v[8:9] op_sel_hi:[1,0]
	v_pk_mul_f32 v[0:1], v[2:3], v[8:9] op_sel_hi:[1,0]
	v_pk_mul_f32 v[4:5], v[118:119], v[4:5]
	v_pk_mul_f32 v[0:1], v[114:115], v[0:1]
	v_pk_mul_f32 v[2:3], v[112:113], v[10:11]
	s_cbranch_vccnz .LBB0_439
	v_mov_b32_e32 v8, v6
	v_mov_b32_e32 v10, v6
	v_mov_b32_e32 v12, v2
	v_mov_b32_e32 v13, v2
	v_permlane32_swap_b32_e32 v8, v10
	s_nop 0
	v_permlane32_swap_b32_e32 v12, v13
	v_mov_b32_e32 v9, v7
	v_mov_b32_e32 v11, v7
	v_mov_b32_e32 v14, v3
	v_mov_b32_e32 v15, v3
	v_cndmask_b32_e64 v8, v8, v10, s[2:3]
	v_cndmask_b32_e64 v10, v12, v13, s[2:3]
	v_mov_b32_e32 v12, v4
	v_mov_b32_e32 v13, v4
	v_permlane32_swap_b32_e32 v9, v11
	v_permlane32_swap_b32_e32 v14, v15
	v_permlane32_swap_b32_e32 v12, v13
	v_cndmask_b32_e64 v9, v9, v11, s[2:3]
	v_cndmask_b32_e64 v11, v14, v15, s[2:3]
	v_cndmask_b32_e64 v12, v12, v13, s[2:3]
	v_mov_b32_e32 v13, v0
	v_mov_b32_e32 v14, v0
	s_nop 1
	v_permlane32_swap_b32_e32 v13, v14
	v_cndmask_b32_e64 v13, v13, v14, s[2:3]
	v_mul_f32_e32 v14, v142, v13
	v_mov_b32_e32 v13, v5
	v_mov_b32_e32 v15, v5
	s_nop 1
	v_permlane32_swap_b32_e32 v13, v15
	v_cndmask_b32_e64 v17, v13, v15, s[2:3]
	v_mov_b32_e32 v13, v1
	v_mov_b32_e32 v15, v1
	s_nop 1
	v_permlane32_swap_b32_e32 v13, v15
	s_waitcnt vmcnt(1)
	v_pk_mul_f32 v[6:7], v[132:133], v[6:7]
	v_mul_f32_e32 v12, v138, v12
	v_cndmask_b32_e64 v19, v13, v15, s[2:3]
	v_mov_b32_e32 v138, v135
	v_mov_b32_e32 v16, v5
	v_mov_b32_e32 v142, v127
	v_mov_b32_e32 v18, v1
	v_pk_mul_f32 v[16:17], v[138:139], v[16:17]
	v_pk_fma_f32 v[6:7], v[136:137], v[8:9], v[6:7]
	v_pk_mul_f32 v[8:9], v[142:143], v[18:19]
	v_pk_mul_f32 v[2:3], v[124:125], v[2:3]
	v_mul_f32_e32 v4, v134, v4
	v_mul_f32_e32 v0, v126, v0
	v_mov_b32_e32 v5, v16
	v_mov_b32_e32 v13, v17
	v_mov_b32_e32 v1, v8
	v_mov_b32_e32 v15, v9
	v_pk_add_f32 v[4:5], v[4:5], v[12:13]
	v_pk_fma_f32 v[2:3], v[140:141], v[10:11], v[2:3]
	v_pk_add_f32 v[0:1], v[0:1], v[14:15]
.LBB0_439:
	v_cvt_pk_bf16_f32 v112, v6, v7
	v_cvt_pk_bf16_f32 v113, v4, v5
	v_cvt_pk_bf16_f32 v114, v2, v3
	s_nop 0
	v_cvt_pk_bf16_f32 v115, v0, v1
	s_andn2_b64 vcc, exec, s[4:5]
	s_mov_b64 s[4:5], -1
	global_store_dwordx4 v[174:175], v[112:115], off offset:256 nt
	s_cbranch_vccnz .LBB0_310

.LBB0_1029:
	s_andn2_b64 vcc, exec, s[2:3]
	s_mov_b64 s[2:3], -1
	global_store_dwordx4 v[154:155], v[128:131], off offset:256 nt
	s_cbranch_vccnz .LBB0_1014
	s_branch .LBB0_1096

.LBB0_1032:
	s_cmp_eq_u32 s17, 2
	v_readlane_b32 s52, v254, 16
	s_cselect_b32 s4, s50, 0x16000000
	v_readlane_b32 s58, v254, 22
	v_readlane_b32 s59, v254, 23
	s_add_u32 s4, s58, s4
	s_addc_u32 s5, s59, 0
	s_lshl_b32 s17, s15, 1
	s_add_u32 s4, s4, s17
	s_addc_u32 s5, s5, 0
	s_lshl_b32 s17, s43, 1
	v_lshl_add_u32 v154, s22, 8, v147
	s_add_u32 s4, s4, s17
	s_addc_u32 s5, s5, 0
	v_lshlrev_b32_e32 v144, 1, v146
	v_ashrrev_i32_e32 v155, 31, v154
	v_lshl_add_u64 v[156:157], s[4:5], 0, v[144:145]
	v_lshlrev_b64 v[158:159], 12, v[154:155]
	v_lshl_add_u64 v[158:159], v[156:157], 0, v[158:159]
	v_cvt_pk_bf16_f32 v128, v128, v129
	v_cvt_pk_bf16_f32 v129, v130, v131
	v_cvt_pk_bf16_f32 v130, v132, v133
	v_cvt_pk_bf16_f32 v131, v134, v135
	global_store_dwordx4 v[158:159], v[128:131], off nt
	v_mov_b64_e32 v[134:135], v[118:119]
	s_andn2_b64 vcc, exec, s[26:27]
	v_cndmask_b32_e64 v128, 0, 1, s[26:27]
	v_cmp_ne_u32_e64 s[4:5], 1, v128
	v_mov_b64_e32 v[130:131], v[110:111]
	v_mov_b64_e32 v[128:129], v[108:109]
	v_mov_b64_e32 v[132:133], v[116:117]
	v_readlane_b32 s53, v254, 17
	v_readlane_b32 s54, v254, 18
	v_readlane_b32 s55, v254, 19
	v_readlane_b32 s56, v254, 20
	v_readlane_b32 s57, v254, 21
	s_cbranch_vccnz .LBB0_1034
	v_mul_f32_e32 v129, 0xbfb8aa3b, v116
	v_mul_f32_e32 v130, 0xbfb8aa3b, v109
	v_exp_f32_e32 v129, v129
	v_exp_f32_e32 v130, v130
	v_mul_f32_e32 v131, 0xbfb8aa3b, v110
	v_mul_f32_e32 v133, 0xbfb8aa3b, v118
	v_add_f32_e32 v129, 1.0, v129
	v_rcp_f32_e32 v132, v129
	v_add_f32_e32 v129, 1.0, v130
	v_mul_f32_e32 v130, 0xbfb8aa3b, v117
	v_exp_f32_e32 v130, v130
	v_exp_f32_e32 v131, v131
	v_exp_f32_e32 v133, v133
	v_mul_f32_e32 v128, 0xbfb8aa3b, v108
	v_add_f32_e32 v144, 1.0, v130
	v_add_f32_e32 v130, 1.0, v131
	v_add_f32_e32 v131, 1.0, v133
	v_mul_f32_e32 v133, 0xbfb8aa3b, v111
	v_mul_f32_e32 v134, 0xbfb8aa3b, v119
	v_exp_f32_e32 v128, v128
	v_exp_f32_e32 v133, v133
	v_exp_f32_e32 v135, v134
	v_rcp_f32_e32 v134, v131
	v_add_f32_e32 v128, 1.0, v128
	v_add_f32_e32 v131, 1.0, v133
	v_add_f32_e32 v133, 1.0, v135
	v_rcp_f32_e32 v128, v128
	v_rcp_f32_e32 v129, v129
	v_rcp_f32_e32 v130, v130
	v_rcp_f32_e32 v131, v131
	v_rcp_f32_e32 v135, v133
	v_rcp_f32_e32 v133, v144
	v_pk_mul_f32 v[128:129], v[108:109], v[128:129]
	v_pk_mul_f32 v[130:131], v[110:111], v[130:131]
	v_pk_mul_f32 v[134:135], v[118:119], v[134:135]
	v_pk_mul_f32 v[132:133], v[116:117], v[132:133]
.LBB0_1034:
	v_cvt_pk_bf16_f32 v128, v128, v129
	v_cvt_pk_bf16_f32 v129, v130, v131
	s_nop 0
	v_cvt_pk_bf16_f32 v130, v132, v133
	v_cvt_pk_bf16_f32 v131, v134, v135
	global_store_dwordx4 v[158:159], v[128:131], off offset:256 nt
	v_mov_b64_e32 v[134:135], v[114:115]
	s_and_b64 vcc, exec, s[4:5]
	v_mov_b64_e32 v[130:131], v[102:103]
	v_mov_b64_e32 v[128:129], v[100:101]
	v_mov_b64_e32 v[132:133], v[112:113]
	s_cbranch_vccnz .LBB0_1036
	v_mul_f32_e32 v129, 0xbfb8aa3b, v112
	v_mul_f32_e32 v130, 0xbfb8aa3b, v101
	v_exp_f32_e32 v129, v129
	v_exp_f32_e32 v130, v130
	v_mul_f32_e32 v131, 0xbfb8aa3b, v102
	v_mul_f32_e32 v133, 0xbfb8aa3b, v114
	v_add_f32_e32 v129, 1.0, v129
	v_rcp_f32_e32 v132, v129
	v_add_f32_e32 v129, 1.0, v130
	v_mul_f32_e32 v130, 0xbfb8aa3b, v113
	v_exp_f32_e32 v130, v130
	v_exp_f32_e32 v131, v131
	v_exp_f32_e32 v133, v133
	v_mul_f32_e32 v128, 0xbfb8aa3b, v100
	v_add_f32_e32 v144, 1.0, v130
	v_add_f32_e32 v130, 1.0, v131
	v_add_f32_e32 v131, 1.0, v133
	v_mul_f32_e32 v133, 0xbfb8aa3b, v103
	v_mul_f32_e32 v134, 0xbfb8aa3b, v115
	v_exp_f32_e32 v128, v128
	v_exp_f32_e32 v133, v133
	v_exp_f32_e32 v135, v134
	v_rcp_f32_e32 v134, v131
	v_add_f32_e32 v128, 1.0, v128
	v_add_f32_e32 v131, 1.0, v133
	v_add_f32_e32 v133, 1.0, v135
	v_rcp_f32_e32 v128, v128
	v_rcp_f32_e32 v129, v129
	v_rcp_f32_e32 v130, v130
	v_rcp_f32_e32 v131, v131
	v_rcp_f32_e32 v135, v133
	v_rcp_f32_e32 v133, v144
	v_pk_mul_f32 v[128:129], v[100:101], v[128:129]
	v_pk_mul_f32 v[130:131], v[102:103], v[130:131]
	v_pk_mul_f32 v[134:135], v[114:115], v[134:135]
	v_pk_mul_f32 v[132:133], v[112:113], v[132:133]
.LBB0_1036:
	v_or_b32_e32 v158, 16, v154
	v_ashrrev_i32_e32 v159, 31, v158
	v_lshlrev_b64 v[158:159], 12, v[158:159]
	v_lshl_add_u64 v[158:159], v[156:157], 0, v[158:159]
	v_cvt_pk_bf16_f32 v128, v128, v129
	v_cvt_pk_bf16_f32 v129, v130, v131
	v_cvt_pk_bf16_f32 v130, v132, v133
	v_cvt_pk_bf16_f32 v131, v134, v135
	global_store_dwordx4 v[158:159], v[128:131], off nt
	v_mov_b64_e32 v[134:135], v[106:107]
	s_and_b64 vcc, exec, s[4:5]
	v_mov_b64_e32 v[130:131], v[94:95]
	v_mov_b64_e32 v[128:129], v[92:93]
	v_mov_b64_e32 v[132:133], v[104:105]
	s_cbranch_vccnz .LBB0_1038
	v_mul_f32_e32 v129, 0xbfb8aa3b, v104
	v_mul_f32_e32 v130, 0xbfb8aa3b, v93
	v_exp_f32_e32 v129, v129
	v_exp_f32_e32 v130, v130
	v_mul_f32_e32 v131, 0xbfb8aa3b, v94
	v_mul_f32_e32 v133, 0xbfb8aa3b, v106
	v_add_f32_e32 v129, 1.0, v129
	v_rcp_f32_e32 v132, v129
	v_add_f32_e32 v129, 1.0, v130
	v_mul_f32_e32 v130, 0xbfb8aa3b, v105
	v_exp_f32_e32 v130, v130
	v_exp_f32_e32 v131, v131
	v_exp_f32_e32 v133, v133
	v_mul_f32_e32 v128, 0xbfb8aa3b, v92
	v_add_f32_e32 v144, 1.0, v130
	v_add_f32_e32 v130, 1.0, v131
	v_add_f32_e32 v131, 1.0, v133
	v_mul_f32_e32 v133, 0xbfb8aa3b, v95
	v_mul_f32_e32 v134, 0xbfb8aa3b, v107
	v_exp_f32_e32 v128, v128
	v_exp_f32_e32 v133, v133
	v_exp_f32_e32 v135, v134
	v_rcp_f32_e32 v134, v131
	v_add_f32_e32 v128, 1.0, v128
	v_add_f32_e32 v131, 1.0, v133
	v_add_f32_e32 v133, 1.0, v135
	v_rcp_f32_e32 v128, v128
	v_rcp_f32_e32 v129, v129
	v_rcp_f32_e32 v130, v130
	v_rcp_f32_e32 v131, v131
	v_rcp_f32_e32 v135, v133
	v_rcp_f32_e32 v133, v144
	v_pk_mul_f32 v[128:129], v[92:93], v[128:129]
	v_pk_mul_f32 v[130:131], v[94:95], v[130:131]
	v_pk_mul_f32 v[134:135], v[106:107], v[134:135]
	v_pk_mul_f32 v[132:133], v[104:105], v[132:133]
.LBB0_1038:
	v_cvt_pk_bf16_f32 v128, v128, v129
	v_cvt_pk_bf16_f32 v129, v130, v131
	s_nop 0
	v_cvt_pk_bf16_f32 v130, v132, v133
	v_cvt_pk_bf16_f32 v131, v134, v135
	global_store_dwordx4 v[158:159], v[128:131], off offset:256 nt
	v_mov_b64_e32 v[134:135], v[98:99]
	s_and_b64 vcc, exec, s[4:5]
	v_mov_b64_e32 v[130:131], v[86:87]
	v_mov_b64_e32 v[128:129], v[84:85]
	v_mov_b64_e32 v[132:133], v[96:97]
	s_cbranch_vccnz .LBB0_1040
	v_mul_f32_e32 v129, 0xbfb8aa3b, v96
	v_mul_f32_e32 v130, 0xbfb8aa3b, v85
	v_exp_f32_e32 v129, v129
	v_exp_f32_e32 v130, v130
	v_mul_f32_e32 v131, 0xbfb8aa3b, v86
	v_mul_f32_e32 v133, 0xbfb8aa3b, v98
	v_add_f32_e32 v129, 1.0, v129
	v_rcp_f32_e32 v132, v129
	v_add_f32_e32 v129, 1.0, v130
	v_mul_f32_e32 v130, 0xbfb8aa3b, v97
	v_exp_f32_e32 v130, v130
	v_exp_f32_e32 v131, v131
	v_exp_f32_e32 v133, v133
	v_mul_f32_e32 v128, 0xbfb8aa3b, v84
	v_add_f32_e32 v144, 1.0, v130
	v_add_f32_e32 v130, 1.0, v131
	v_add_f32_e32 v131, 1.0, v133
	v_mul_f32_e32 v133, 0xbfb8aa3b, v87
	v_mul_f32_e32 v134, 0xbfb8aa3b, v99
	v_exp_f32_e32 v128, v128
	v_exp_f32_e32 v133, v133
	v_exp_f32_e32 v135, v134
	v_rcp_f32_e32 v134, v131
	v_add_f32_e32 v128, 1.0, v128
	v_add_f32_e32 v131, 1.0, v133
	v_add_f32_e32 v133, 1.0, v135
	v_rcp_f32_e32 v128, v128
	v_rcp_f32_e32 v129, v129
	v_rcp_f32_e32 v130, v130
	v_rcp_f32_e32 v131, v131
	v_rcp_f32_e32 v135, v133
	v_rcp_f32_e32 v133, v144
	v_pk_mul_f32 v[128:129], v[84:85], v[128:129]
	v_pk_mul_f32 v[130:131], v[86:87], v[130:131]
	v_pk_mul_f32 v[134:135], v[98:99], v[134:135]
	v_pk_mul_f32 v[132:133], v[96:97], v[132:133]
.LBB0_1040:
	v_or_b32_e32 v158, 32, v154
	v_ashrrev_i32_e32 v159, 31, v158
	v_lshlrev_b64 v[158:159], 12, v[158:159]
	v_lshl_add_u64 v[158:159], v[156:157], 0, v[158:159]
	v_cvt_pk_bf16_f32 v128, v128, v129
	v_cvt_pk_bf16_f32 v129, v130, v131
	v_cvt_pk_bf16_f32 v130, v132, v133
	v_cvt_pk_bf16_f32 v131, v134, v135
	global_store_dwordx4 v[158:159], v[128:131], off nt
	v_mov_b64_e32 v[134:135], v[90:91]
	s_and_b64 vcc, exec, s[4:5]
	v_mov_b64_e32 v[130:131], v[78:79]
	v_mov_b64_e32 v[128:129], v[76:77]
	v_mov_b64_e32 v[132:133], v[88:89]
	s_cbranch_vccnz .LBB0_1042
	v_mul_f32_e32 v129, 0xbfb8aa3b, v88
	v_mul_f32_e32 v130, 0xbfb8aa3b, v77
	v_exp_f32_e32 v129, v129
	v_exp_f32_e32 v130, v130
	v_mul_f32_e32 v131, 0xbfb8aa3b, v78
	v_mul_f32_e32 v133, 0xbfb8aa3b, v90
	v_add_f32_e32 v129, 1.0, v129
	v_rcp_f32_e32 v132, v129
	v_add_f32_e32 v129, 1.0, v130
	v_mul_f32_e32 v130, 0xbfb8aa3b, v89
	v_exp_f32_e32 v130, v130
	v_exp_f32_e32 v131, v131
	v_exp_f32_e32 v133, v133
	v_mul_f32_e32 v128, 0xbfb8aa3b, v76
	v_add_f32_e32 v144, 1.0, v130
	v_add_f32_e32 v130, 1.0, v131
	v_add_f32_e32 v131, 1.0, v133
	v_mul_f32_e32 v133, 0xbfb8aa3b, v79
	v_mul_f32_e32 v134, 0xbfb8aa3b, v91
	v_exp_f32_e32 v128, v128
	v_exp_f32_e32 v133, v133
	v_exp_f32_e32 v135, v134
	v_rcp_f32_e32 v134, v131
	v_add_f32_e32 v128, 1.0, v128
	v_add_f32_e32 v131, 1.0, v133
	v_add_f32_e32 v133, 1.0, v135
	v_rcp_f32_e32 v128, v128
	v_rcp_f32_e32 v129, v129
	v_rcp_f32_e32 v130, v130
	v_rcp_f32_e32 v131, v131
	v_rcp_f32_e32 v135, v133
	v_rcp_f32_e32 v133, v144
	v_pk_mul_f32 v[128:129], v[76:77], v[128:129]
	v_pk_mul_f32 v[130:131], v[78:79], v[130:131]
	v_pk_mul_f32 v[134:135], v[90:91], v[134:135]
	v_pk_mul_f32 v[132:133], v[88:89], v[132:133]
.LBB0_1042:
	v_cvt_pk_bf16_f32 v128, v128, v129
	v_cvt_pk_bf16_f32 v129, v130, v131
	s_nop 0
	v_cvt_pk_bf16_f32 v130, v132, v133
	v_cvt_pk_bf16_f32 v131, v134, v135
	global_store_dwordx4 v[158:159], v[128:131], off offset:256 nt
	v_mov_b64_e32 v[134:135], v[82:83]
	s_and_b64 vcc, exec, s[4:5]
	v_mov_b64_e32 v[130:131], v[70:71]
	v_mov_b64_e32 v[128:129], v[68:69]
	v_mov_b64_e32 v[132:133], v[80:81]
	s_cbranch_vccnz .LBB0_1044
	v_mul_f32_e32 v129, 0xbfb8aa3b, v80
	v_mul_f32_e32 v130, 0xbfb8aa3b, v69
	v_exp_f32_e32 v129, v129
	v_exp_f32_e32 v130, v130
	v_mul_f32_e32 v131, 0xbfb8aa3b, v70
	v_mul_f32_e32 v133, 0xbfb8aa3b, v82
	v_add_f32_e32 v129, 1.0, v129
	v_rcp_f32_e32 v132, v129
	v_add_f32_e32 v129, 1.0, v130
	v_mul_f32_e32 v130, 0xbfb8aa3b, v81
	v_exp_f32_e32 v130, v130
	v_exp_f32_e32 v131, v131
	v_exp_f32_e32 v133, v133
	v_mul_f32_e32 v128, 0xbfb8aa3b, v68
	v_add_f32_e32 v144, 1.0, v130
	v_add_f32_e32 v130, 1.0, v131
	v_add_f32_e32 v131, 1.0, v133
	v_mul_f32_e32 v133, 0xbfb8aa3b, v71
	v_mul_f32_e32 v134, 0xbfb8aa3b, v83
	v_exp_f32_e32 v128, v128
	v_exp_f32_e32 v133, v133
	v_exp_f32_e32 v135, v134
	v_rcp_f32_e32 v134, v131
	v_add_f32_e32 v128, 1.0, v128
	v_add_f32_e32 v131, 1.0, v133
	v_add_f32_e32 v133, 1.0, v135
	v_rcp_f32_e32 v128, v128
	v_rcp_f32_e32 v129, v129
	v_rcp_f32_e32 v130, v130
	v_rcp_f32_e32 v131, v131
	v_rcp_f32_e32 v135, v133
	v_rcp_f32_e32 v133, v144
	v_pk_mul_f32 v[128:129], v[68:69], v[128:129]
	v_pk_mul_f32 v[130:131], v[70:71], v[130:131]
	v_pk_mul_f32 v[134:135], v[82:83], v[134:135]
	v_pk_mul_f32 v[132:133], v[80:81], v[132:133]
.LBB0_1044:
	v_or_b32_e32 v158, 48, v154
	v_ashrrev_i32_e32 v159, 31, v158
	v_lshlrev_b64 v[158:159], 12, v[158:159]
	v_lshl_add_u64 v[158:159], v[156:157], 0, v[158:159]
	v_cvt_pk_bf16_f32 v128, v128, v129
	v_cvt_pk_bf16_f32 v129, v130, v131
	v_cvt_pk_bf16_f32 v130, v132, v133
	v_cvt_pk_bf16_f32 v131, v134, v135
	global_store_dwordx4 v[158:159], v[128:131], off nt
	v_mov_b64_e32 v[134:135], v[74:75]
	s_and_b64 vcc, exec, s[4:5]
	v_mov_b64_e32 v[130:131], v[62:63]
	v_mov_b64_e32 v[128:129], v[60:61]
	v_mov_b64_e32 v[132:133], v[72:73]
	s_cbranch_vccnz .LBB0_1046
	v_mul_f32_e32 v129, 0xbfb8aa3b, v72
	v_mul_f32_e32 v130, 0xbfb8aa3b, v61
	v_exp_f32_e32 v129, v129
	v_exp_f32_e32 v130, v130
	v_mul_f32_e32 v131, 0xbfb8aa3b, v62
	v_mul_f32_e32 v133, 0xbfb8aa3b, v74
	v_add_f32_e32 v129, 1.0, v129
	v_rcp_f32_e32 v132, v129
	v_add_f32_e32 v129, 1.0, v130
	v_mul_f32_e32 v130, 0xbfb8aa3b, v73
	v_exp_f32_e32 v130, v130
	v_exp_f32_e32 v131, v131
	v_exp_f32_e32 v133, v133
	v_mul_f32_e32 v128, 0xbfb8aa3b, v60
	v_add_f32_e32 v144, 1.0, v130
	v_add_f32_e32 v130, 1.0, v131
	v_add_f32_e32 v131, 1.0, v133
	v_mul_f32_e32 v133, 0xbfb8aa3b, v63
	v_mul_f32_e32 v134, 0xbfb8aa3b, v75
	v_exp_f32_e32 v128, v128
	v_exp_f32_e32 v133, v133
	v_exp_f32_e32 v135, v134
	v_rcp_f32_e32 v134, v131
	v_add_f32_e32 v128, 1.0, v128
	v_add_f32_e32 v131, 1.0, v133
	v_add_f32_e32 v133, 1.0, v135
	v_rcp_f32_e32 v128, v128
	v_rcp_f32_e32 v129, v129
	v_rcp_f32_e32 v130, v130
	v_rcp_f32_e32 v131, v131
	v_rcp_f32_e32 v135, v133
	v_rcp_f32_e32 v133, v144
	v_pk_mul_f32 v[128:129], v[60:61], v[128:129]
	v_pk_mul_f32 v[130:131], v[62:63], v[130:131]
	v_pk_mul_f32 v[134:135], v[74:75], v[134:135]
	v_pk_mul_f32 v[132:133], v[72:73], v[132:133]
.LBB0_1046:
	v_cvt_pk_bf16_f32 v128, v128, v129
	v_cvt_pk_bf16_f32 v129, v130, v131
	s_nop 0
	v_cvt_pk_bf16_f32 v130, v132, v133
	v_cvt_pk_bf16_f32 v131, v134, v135
	global_store_dwordx4 v[158:159], v[128:131], off offset:256 nt
	v_mov_b64_e32 v[134:135], v[66:67]
	s_and_b64 vcc, exec, s[4:5]
	v_mov_b64_e32 v[130:131], v[54:55]
	v_mov_b64_e32 v[128:129], v[52:53]
	v_mov_b64_e32 v[132:133], v[64:65]
	s_cbranch_vccnz .LBB0_1048
	v_mul_f32_e32 v129, 0xbfb8aa3b, v64
	v_mul_f32_e32 v130, 0xbfb8aa3b, v53
	v_exp_f32_e32 v129, v129
	v_exp_f32_e32 v130, v130
	v_mul_f32_e32 v131, 0xbfb8aa3b, v54
	v_mul_f32_e32 v133, 0xbfb8aa3b, v66
	v_add_f32_e32 v129, 1.0, v129
	v_rcp_f32_e32 v132, v129
	v_add_f32_e32 v129, 1.0, v130
	v_mul_f32_e32 v130, 0xbfb8aa3b, v65
	v_exp_f32_e32 v130, v130
	v_exp_f32_e32 v131, v131
	v_exp_f32_e32 v133, v133
	v_mul_f32_e32 v128, 0xbfb8aa3b, v52
	v_add_f32_e32 v144, 1.0, v130
	v_add_f32_e32 v130, 1.0, v131
	v_add_f32_e32 v131, 1.0, v133
	v_mul_f32_e32 v133, 0xbfb8aa3b, v55
	v_mul_f32_e32 v134, 0xbfb8aa3b, v67
	v_exp_f32_e32 v128, v128
	v_exp_f32_e32 v133, v133
	v_exp_f32_e32 v135, v134
	v_rcp_f32_e32 v134, v131
	v_add_f32_e32 v128, 1.0, v128
	v_add_f32_e32 v131, 1.0, v133
	v_add_f32_e32 v133, 1.0, v135
	v_rcp_f32_e32 v128, v128
	v_rcp_f32_e32 v129, v129
	v_rcp_f32_e32 v130, v130
	v_rcp_f32_e32 v131, v131
	v_rcp_f32_e32 v135, v133
	v_rcp_f32_e32 v133, v144
	v_pk_mul_f32 v[128:129], v[52:53], v[128:129]
	v_pk_mul_f32 v[130:131], v[54:55], v[130:131]
	v_pk_mul_f32 v[134:135], v[66:67], v[134:135]
	v_pk_mul_f32 v[132:133], v[64:65], v[132:133]
.LBB0_1048:
	v_add_u32_e32 v158, 0x80, v154
	v_ashrrev_i32_e32 v159, 31, v158
	v_lshlrev_b64 v[158:159], 12, v[158:159]
	v_lshl_add_u64 v[158:159], v[156:157], 0, v[158:159]
	v_cvt_pk_bf16_f32 v128, v128, v129
	v_cvt_pk_bf16_f32 v129, v130, v131
	v_cvt_pk_bf16_f32 v130, v132, v133
	v_cvt_pk_bf16_f32 v131, v134, v135
	global_store_dwordx4 v[158:159], v[128:131], off nt
	v_mov_b64_e32 v[134:135], v[58:59]
	s_and_b64 vcc, exec, s[4:5]
	v_mov_b64_e32 v[130:131], v[46:47]
	v_mov_b64_e32 v[128:129], v[44:45]
	v_mov_b64_e32 v[132:133], v[56:57]
	s_cbranch_vccnz .LBB0_1050
	v_mul_f32_e32 v129, 0xbfb8aa3b, v56
	v_mul_f32_e32 v130, 0xbfb8aa3b, v45
	v_exp_f32_e32 v129, v129
	v_exp_f32_e32 v130, v130
	v_mul_f32_e32 v131, 0xbfb8aa3b, v46
	v_mul_f32_e32 v133, 0xbfb8aa3b, v58
	v_add_f32_e32 v129, 1.0, v129
	v_rcp_f32_e32 v132, v129
	v_add_f32_e32 v129, 1.0, v130
	v_mul_f32_e32 v130, 0xbfb8aa3b, v57
	v_exp_f32_e32 v130, v130
	v_exp_f32_e32 v131, v131
	v_exp_f32_e32 v133, v133
	v_mul_f32_e32 v128, 0xbfb8aa3b, v44
	v_add_f32_e32 v144, 1.0, v130
	v_add_f32_e32 v130, 1.0, v131
	v_add_f32_e32 v131, 1.0, v133
	v_mul_f32_e32 v133, 0xbfb8aa3b, v47
	v_mul_f32_e32 v134, 0xbfb8aa3b, v59
	v_exp_f32_e32 v128, v128
	v_exp_f32_e32 v133, v133
	v_exp_f32_e32 v135, v134
	v_rcp_f32_e32 v134, v131
	v_add_f32_e32 v128, 1.0, v128
	v_add_f32_e32 v131, 1.0, v133
	v_add_f32_e32 v133, 1.0, v135
	v_rcp_f32_e32 v128, v128
	v_rcp_f32_e32 v129, v129
	v_rcp_f32_e32 v130, v130
	v_rcp_f32_e32 v131, v131
	v_rcp_f32_e32 v135, v133
	v_rcp_f32_e32 v133, v144
	v_pk_mul_f32 v[128:129], v[44:45], v[128:129]
	v_pk_mul_f32 v[130:131], v[46:47], v[130:131]
	v_pk_mul_f32 v[134:135], v[58:59], v[134:135]
	v_pk_mul_f32 v[132:133], v[56:57], v[132:133]
.LBB0_1050:
	v_cvt_pk_bf16_f32 v128, v128, v129
	v_cvt_pk_bf16_f32 v129, v130, v131
	s_nop 0
	v_cvt_pk_bf16_f32 v130, v132, v133
	v_cvt_pk_bf16_f32 v131, v134, v135
	global_store_dwordx4 v[158:159], v[128:131], off offset:256 nt
	v_mov_b64_e32 v[134:135], v[50:51]
	s_and_b64 vcc, exec, s[4:5]
	v_mov_b64_e32 v[130:131], v[38:39]
	v_mov_b64_e32 v[128:129], v[36:37]
	v_mov_b64_e32 v[132:133], v[48:49]
	s_cbranch_vccnz .LBB0_1052
	v_mul_f32_e32 v129, 0xbfb8aa3b, v48
	v_mul_f32_e32 v130, 0xbfb8aa3b, v37
	v_exp_f32_e32 v129, v129
	v_exp_f32_e32 v130, v130
	v_mul_f32_e32 v131, 0xbfb8aa3b, v38
	v_mul_f32_e32 v133, 0xbfb8aa3b, v50
	v_add_f32_e32 v129, 1.0, v129
	v_rcp_f32_e32 v132, v129
	v_add_f32_e32 v129, 1.0, v130
	v_mul_f32_e32 v130, 0xbfb8aa3b, v49
	v_exp_f32_e32 v130, v130
	v_exp_f32_e32 v131, v131
	v_exp_f32_e32 v133, v133
	v_mul_f32_e32 v128, 0xbfb8aa3b, v36
	v_add_f32_e32 v144, 1.0, v130
	v_add_f32_e32 v130, 1.0, v131
	v_add_f32_e32 v131, 1.0, v133
	v_mul_f32_e32 v133, 0xbfb8aa3b, v39
	v_mul_f32_e32 v134, 0xbfb8aa3b, v51
	v_exp_f32_e32 v128, v128
	v_exp_f32_e32 v133, v133
	v_exp_f32_e32 v135, v134
	v_rcp_f32_e32 v134, v131
	v_add_f32_e32 v128, 1.0, v128
	v_add_f32_e32 v131, 1.0, v133
	v_add_f32_e32 v133, 1.0, v135
	v_rcp_f32_e32 v128, v128
	v_rcp_f32_e32 v129, v129
	v_rcp_f32_e32 v130, v130
	v_rcp_f32_e32 v131, v131
	v_rcp_f32_e32 v135, v133
	v_rcp_f32_e32 v133, v144
	v_pk_mul_f32 v[128:129], v[36:37], v[128:129]
	v_pk_mul_f32 v[130:131], v[38:39], v[130:131]
	v_pk_mul_f32 v[134:135], v[50:51], v[134:135]
	v_pk_mul_f32 v[132:133], v[48:49], v[132:133]
.LBB0_1052:
	v_add_u32_e32 v158, 0x90, v154
	v_ashrrev_i32_e32 v159, 31, v158
	v_lshlrev_b64 v[158:159], 12, v[158:159]
	v_lshl_add_u64 v[158:159], v[156:157], 0, v[158:159]
	v_cvt_pk_bf16_f32 v128, v128, v129
	v_cvt_pk_bf16_f32 v129, v130, v131
	v_cvt_pk_bf16_f32 v130, v132, v133
	v_cvt_pk_bf16_f32 v131, v134, v135
	global_store_dwordx4 v[158:159], v[128:131], off nt
	v_mov_b64_e32 v[134:135], v[42:43]
	s_and_b64 vcc, exec, s[4:5]
	v_mov_b64_e32 v[130:131], v[30:31]
	v_mov_b64_e32 v[128:129], v[28:29]
	v_mov_b64_e32 v[132:133], v[40:41]
	s_cbranch_vccnz .LBB0_1054
	v_mul_f32_e32 v129, 0xbfb8aa3b, v40
	v_mul_f32_e32 v130, 0xbfb8aa3b, v29
	v_exp_f32_e32 v129, v129
	v_exp_f32_e32 v130, v130
	v_mul_f32_e32 v131, 0xbfb8aa3b, v30
	v_mul_f32_e32 v133, 0xbfb8aa3b, v42
	v_add_f32_e32 v129, 1.0, v129
	v_rcp_f32_e32 v132, v129
	v_add_f32_e32 v129, 1.0, v130
	v_mul_f32_e32 v130, 0xbfb8aa3b, v41
	v_exp_f32_e32 v130, v130
	v_exp_f32_e32 v131, v131
	v_exp_f32_e32 v133, v133
	v_mul_f32_e32 v128, 0xbfb8aa3b, v28
	v_add_f32_e32 v144, 1.0, v130
	v_add_f32_e32 v130, 1.0, v131
	v_add_f32_e32 v131, 1.0, v133
	v_mul_f32_e32 v133, 0xbfb8aa3b, v31
	v_mul_f32_e32 v134, 0xbfb8aa3b, v43
	v_exp_f32_e32 v128, v128
	v_exp_f32_e32 v133, v133
	v_exp_f32_e32 v135, v134
	v_rcp_f32_e32 v134, v131
	v_add_f32_e32 v128, 1.0, v128
	v_add_f32_e32 v131, 1.0, v133
	v_add_f32_e32 v133, 1.0, v135
	v_rcp_f32_e32 v128, v128
	v_rcp_f32_e32 v129, v129
	v_rcp_f32_e32 v130, v130
	v_rcp_f32_e32 v131, v131
	v_rcp_f32_e32 v135, v133
	v_rcp_f32_e32 v133, v144
	v_pk_mul_f32 v[128:129], v[28:29], v[128:129]
	v_pk_mul_f32 v[130:131], v[30:31], v[130:131]
	v_pk_mul_f32 v[134:135], v[42:43], v[134:135]
	v_pk_mul_f32 v[132:133], v[40:41], v[132:133]
.LBB0_1054:
	v_cvt_pk_bf16_f32 v128, v128, v129
	v_cvt_pk_bf16_f32 v129, v130, v131
	s_nop 0
	v_cvt_pk_bf16_f32 v130, v132, v133
	v_cvt_pk_bf16_f32 v131, v134, v135
	global_store_dwordx4 v[158:159], v[128:131], off offset:256 nt
	v_mov_b64_e32 v[134:135], v[34:35]
	s_and_b64 vcc, exec, s[4:5]
	v_mov_b64_e32 v[130:131], v[22:23]
	v_mov_b64_e32 v[128:129], v[20:21]
	v_mov_b64_e32 v[132:133], v[32:33]
	s_cbranch_vccnz .LBB0_1056
	v_mul_f32_e32 v129, 0xbfb8aa3b, v32
	v_mul_f32_e32 v130, 0xbfb8aa3b, v21
	v_exp_f32_e32 v129, v129
	v_exp_f32_e32 v130, v130
	v_mul_f32_e32 v131, 0xbfb8aa3b, v22
	v_mul_f32_e32 v133, 0xbfb8aa3b, v34
	v_add_f32_e32 v129, 1.0, v129
	v_rcp_f32_e32 v132, v129
	v_add_f32_e32 v129, 1.0, v130
	v_mul_f32_e32 v130, 0xbfb8aa3b, v33
	v_exp_f32_e32 v130, v130
	v_exp_f32_e32 v131, v131
	v_exp_f32_e32 v133, v133
	v_mul_f32_e32 v128, 0xbfb8aa3b, v20
	v_add_f32_e32 v144, 1.0, v130
	v_add_f32_e32 v130, 1.0, v131
	v_add_f32_e32 v131, 1.0, v133
	v_mul_f32_e32 v133, 0xbfb8aa3b, v23
	v_mul_f32_e32 v134, 0xbfb8aa3b, v35
	v_exp_f32_e32 v128, v128
	v_exp_f32_e32 v133, v133
	v_exp_f32_e32 v135, v134
	v_rcp_f32_e32 v134, v131
	v_add_f32_e32 v128, 1.0, v128
	v_add_f32_e32 v131, 1.0, v133
	v_add_f32_e32 v133, 1.0, v135
	v_rcp_f32_e32 v128, v128
	v_rcp_f32_e32 v129, v129
	v_rcp_f32_e32 v130, v130
	v_rcp_f32_e32 v131, v131
	v_rcp_f32_e32 v135, v133
	v_rcp_f32_e32 v133, v144
	v_pk_mul_f32 v[128:129], v[20:21], v[128:129]
	v_pk_mul_f32 v[130:131], v[22:23], v[130:131]
	v_pk_mul_f32 v[134:135], v[34:35], v[134:135]
	v_pk_mul_f32 v[132:133], v[32:33], v[132:133]
.LBB0_1056:
	v_add_u32_e32 v158, 0xa0, v154
	v_ashrrev_i32_e32 v159, 31, v158
	v_lshlrev_b64 v[158:159], 12, v[158:159]
	v_lshl_add_u64 v[158:159], v[156:157], 0, v[158:159]
	v_cvt_pk_bf16_f32 v128, v128, v129
	v_cvt_pk_bf16_f32 v129, v130, v131
	v_cvt_pk_bf16_f32 v130, v132, v133
	v_cvt_pk_bf16_f32 v131, v134, v135
	global_store_dwordx4 v[158:159], v[128:131], off nt
	v_mov_b64_e32 v[134:135], v[26:27]
	s_and_b64 vcc, exec, s[4:5]
	v_mov_b64_e32 v[130:131], v[18:19]
	v_mov_b64_e32 v[128:129], v[16:17]
	v_mov_b64_e32 v[132:133], v[24:25]
	s_cbranch_vccnz .LBB0_1058
	v_mul_f32_e32 v129, 0xbfb8aa3b, v24
	v_mul_f32_e32 v130, 0xbfb8aa3b, v17
	v_exp_f32_e32 v129, v129
	v_exp_f32_e32 v130, v130
	v_mul_f32_e32 v131, 0xbfb8aa3b, v18
	v_mul_f32_e32 v133, 0xbfb8aa3b, v26
	v_add_f32_e32 v129, 1.0, v129
	v_rcp_f32_e32 v132, v129
	v_add_f32_e32 v129, 1.0, v130
	v_mul_f32_e32 v130, 0xbfb8aa3b, v25
	v_exp_f32_e32 v130, v130
	v_exp_f32_e32 v131, v131
	v_exp_f32_e32 v133, v133
	v_mul_f32_e32 v128, 0xbfb8aa3b, v16
	v_add_f32_e32 v144, 1.0, v130
	v_add_f32_e32 v130, 1.0, v131
	v_add_f32_e32 v131, 1.0, v133
	v_mul_f32_e32 v133, 0xbfb8aa3b, v19
	v_mul_f32_e32 v134, 0xbfb8aa3b, v27
	v_exp_f32_e32 v128, v128
	v_exp_f32_e32 v133, v133
	v_exp_f32_e32 v135, v134
	v_rcp_f32_e32 v134, v131
	v_add_f32_e32 v128, 1.0, v128
	v_add_f32_e32 v131, 1.0, v133
	v_add_f32_e32 v133, 1.0, v135
	v_rcp_f32_e32 v128, v128
	v_rcp_f32_e32 v129, v129
	v_rcp_f32_e32 v130, v130
	v_rcp_f32_e32 v131, v131
	v_rcp_f32_e32 v135, v133
	v_rcp_f32_e32 v133, v144
	v_pk_mul_f32 v[128:129], v[16:17], v[128:129]
	v_pk_mul_f32 v[130:131], v[18:19], v[130:131]
	v_pk_mul_f32 v[134:135], v[26:27], v[134:135]
	v_pk_mul_f32 v[132:133], v[24:25], v[132:133]
.LBB0_1058:
	v_cvt_pk_bf16_f32 v128, v128, v129
	v_cvt_pk_bf16_f32 v129, v130, v131
	s_nop 0
	v_cvt_pk_bf16_f32 v130, v132, v133
	v_cvt_pk_bf16_f32 v131, v134, v135
	global_store_dwordx4 v[158:159], v[128:131], off offset:256 nt
	v_mov_b64_e32 v[134:135], v[14:15]
	s_and_b64 vcc, exec, s[4:5]
	v_mov_b64_e32 v[130:131], v[10:11]
	v_mov_b64_e32 v[128:129], v[8:9]
	v_mov_b64_e32 v[132:133], v[12:13]
	s_cbranch_vccnz .LBB0_1060
	v_mul_f32_e32 v129, 0xbfb8aa3b, v12
	v_mul_f32_e32 v130, 0xbfb8aa3b, v9
	v_exp_f32_e32 v129, v129
	v_exp_f32_e32 v130, v130
	v_mul_f32_e32 v131, 0xbfb8aa3b, v10
	v_mul_f32_e32 v133, 0xbfb8aa3b, v14
	v_add_f32_e32 v129, 1.0, v129
	v_rcp_f32_e32 v132, v129
	v_add_f32_e32 v129, 1.0, v130
	v_mul_f32_e32 v130, 0xbfb8aa3b, v13
	v_exp_f32_e32 v130, v130
	v_exp_f32_e32 v131, v131
	v_exp_f32_e32 v133, v133
	v_mul_f32_e32 v128, 0xbfb8aa3b, v8
	v_add_f32_e32 v144, 1.0, v130
	v_add_f32_e32 v130, 1.0, v131
	v_add_f32_e32 v131, 1.0, v133
	v_mul_f32_e32 v133, 0xbfb8aa3b, v11
	v_mul_f32_e32 v134, 0xbfb8aa3b, v15
	v_exp_f32_e32 v128, v128
	v_exp_f32_e32 v133, v133
	v_exp_f32_e32 v135, v134
	v_rcp_f32_e32 v134, v131
	v_add_f32_e32 v128, 1.0, v128
	v_add_f32_e32 v131, 1.0, v133
	v_add_f32_e32 v133, 1.0, v135
	v_rcp_f32_e32 v128, v128
	v_rcp_f32_e32 v129, v129
	v_rcp_f32_e32 v130, v130
	v_rcp_f32_e32 v131, v131
	v_rcp_f32_e32 v135, v133
	v_rcp_f32_e32 v133, v144
	v_pk_mul_f32 v[128:129], v[8:9], v[128:129]
	v_pk_mul_f32 v[130:131], v[10:11], v[130:131]
	v_pk_mul_f32 v[134:135], v[14:15], v[134:135]
	v_pk_mul_f32 v[132:133], v[12:13], v[132:133]
.LBB0_1060:
	v_add_u32_e32 v154, 0xb0, v154
	v_ashrrev_i32_e32 v155, 31, v154
	v_lshlrev_b64 v[154:155], 12, v[154:155]
	v_lshl_add_u64 v[154:155], v[156:157], 0, v[154:155]
	v_cvt_pk_bf16_f32 v128, v128, v129
	v_cvt_pk_bf16_f32 v129, v130, v131
	v_cvt_pk_bf16_f32 v130, v132, v133
	v_cvt_pk_bf16_f32 v131, v134, v135
	global_store_dwordx4 v[154:155], v[128:131], off nt
	v_mov_b64_e32 v[134:135], v[6:7]
	s_and_b64 vcc, exec, s[4:5]
	v_mov_b64_e32 v[130:131], v[2:3]
	v_mov_b64_e32 v[128:129], v[0:1]
	v_mov_b64_e32 v[132:133], v[4:5]
	s_cbranch_vccnz .LBB0_1062
	v_mul_f32_e32 v129, 0xbfb8aa3b, v4
	v_mul_f32_e32 v130, 0xbfb8aa3b, v1
	v_exp_f32_e32 v129, v129
	v_exp_f32_e32 v130, v130
	v_mul_f32_e32 v131, 0xbfb8aa3b, v2
	v_mul_f32_e32 v133, 0xbfb8aa3b, v6
	v_add_f32_e32 v129, 1.0, v129
	v_rcp_f32_e32 v132, v129
	v_add_f32_e32 v129, 1.0, v130
	v_mul_f32_e32 v130, 0xbfb8aa3b, v5
	v_exp_f32_e32 v130, v130
	v_exp_f32_e32 v131, v131
	v_exp_f32_e32 v133, v133
	v_mul_f32_e32 v128, 0xbfb8aa3b, v0
	v_add_f32_e32 v144, 1.0, v130
	v_add_f32_e32 v130, 1.0, v131
	v_add_f32_e32 v131, 1.0, v133
	v_mul_f32_e32 v133, 0xbfb8aa3b, v3
	v_mul_f32_e32 v134, 0xbfb8aa3b, v7
	v_exp_f32_e32 v128, v128
	v_exp_f32_e32 v133, v133
	v_exp_f32_e32 v135, v134
	v_rcp_f32_e32 v134, v131
	v_add_f32_e32 v128, 1.0, v128
	v_add_f32_e32 v131, 1.0, v133
	v_add_f32_e32 v133, 1.0, v135
	v_rcp_f32_e32 v128, v128
	v_rcp_f32_e32 v129, v129
	v_rcp_f32_e32 v130, v130
	v_rcp_f32_e32 v131, v131
	v_rcp_f32_e32 v135, v133
	v_rcp_f32_e32 v133, v144
	v_pk_mul_f32 v[128:129], v[0:1], v[128:129]
	v_pk_mul_f32 v[130:131], v[2:3], v[130:131]
	v_pk_mul_f32 v[134:135], v[6:7], v[134:135]
	v_pk_mul_f32 v[132:133], v[4:5], v[132:133]

.LBB0_1063:
	v_mul_f32_e32 v128, v121, v121
	v_mul_f32_e32 v129, v123, v123
	v_fmac_f32_e32 v128, v120, v120
	v_fmac_f32_e32 v129, v122, v122
	v_add_f32_e32 v128, v128, v129
	v_mul_f32_e32 v129, v125, v125
	v_fmac_f32_e32 v129, v124, v124
	v_add_f32_e32 v128, v129, v128
	v_mul_f32_e32 v129, v127, v127
	v_fmac_f32_e32 v129, v126, v126
	v_add_f32_e32 v128, v129, v128
	v_mov_b32_e32 v129, v128
	s_nop 1
	v_permlane16_swap_b32_e32 v128, v129
	v_add_f32_e32 v128, v128, v129
	v_mov_b32_e32 v129, v128
	s_nop 1
	v_permlane32_swap_b32_e32 v128, v129
	s_and_saveexec_b64 s[4:5], s[0:1]
	v_add_f32_e32 v128, v128, v129
	ds_write_b32 v170, v128
	s_or_b64 exec, exec, s[4:5]
	v_mul_f32_e32 v128, v109, v109
	v_mul_f32_e32 v129, v111, v111
	v_fmac_f32_e32 v128, v108, v108
	v_fmac_f32_e32 v129, v110, v110
	v_add_f32_e32 v128, v128, v129
	v_mul_f32_e32 v129, v117, v117
	v_fmac_f32_e32 v129, v116, v116
	v_add_f32_e32 v128, v129, v128
	v_mul_f32_e32 v129, v119, v119
	v_fmac_f32_e32 v129, v118, v118
	v_add_f32_e32 v128, v129, v128
	v_mov_b32_e32 v129, v128
	s_nop 1
	v_permlane16_swap_b32_e32 v128, v129
	v_add_f32_e32 v128, v128, v129
	v_mov_b32_e32 v129, v128
	s_nop 1
	v_permlane32_swap_b32_e32 v128, v129
	s_and_saveexec_b64 s[4:5], s[0:1]
	v_add_f32_e32 v128, v128, v129
	ds_write_b32 v170, v128 offset:16
	s_or_b64 exec, exec, s[4:5]
	v_mul_f32_e32 v128, v101, v101
	v_mul_f32_e32 v129, v103, v103
	v_fmac_f32_e32 v128, v100, v100
	v_fmac_f32_e32 v129, v102, v102
	v_add_f32_e32 v128, v128, v129
	v_mul_f32_e32 v129, v113, v113
	v_fmac_f32_e32 v129, v112, v112
	v_add_f32_e32 v128, v129, v128
	v_mul_f32_e32 v129, v115, v115
	v_fmac_f32_e32 v129, v114, v114
	v_add_f32_e32 v128, v129, v128
	v_mov_b32_e32 v129, v128
	s_nop 1
	v_permlane16_swap_b32_e32 v128, v129
	v_add_f32_e32 v128, v128, v129
	v_mov_b32_e32 v129, v128
	s_nop 1
	v_permlane32_swap_b32_e32 v128, v129
	s_and_saveexec_b64 s[4:5], s[0:1]
	v_add_f32_e32 v128, v128, v129
	ds_write_b32 v171, v128
	s_or_b64 exec, exec, s[4:5]
	v_mul_f32_e32 v128, v93, v93
	v_mul_f32_e32 v129, v95, v95
	v_fmac_f32_e32 v128, v92, v92
	v_fmac_f32_e32 v129, v94, v94
	v_add_f32_e32 v128, v128, v129
	v_mul_f32_e32 v129, v105, v105
	v_fmac_f32_e32 v129, v104, v104
	v_add_f32_e32 v128, v129, v128
	v_mul_f32_e32 v129, v107, v107
	v_fmac_f32_e32 v129, v106, v106
	v_add_f32_e32 v128, v129, v128
	v_mov_b32_e32 v129, v128
	s_nop 1
	v_permlane16_swap_b32_e32 v128, v129
	v_add_f32_e32 v128, v128, v129
	v_mov_b32_e32 v129, v128
	s_nop 1
	v_permlane32_swap_b32_e32 v128, v129
	s_and_saveexec_b64 s[4:5], s[0:1]
	v_add_f32_e32 v128, v128, v129
	ds_write_b32 v171, v128 offset:16
	s_or_b64 exec, exec, s[4:5]
	v_mul_f32_e32 v128, v85, v85
	v_mul_f32_e32 v129, v87, v87
	v_fmac_f32_e32 v128, v84, v84
	v_fmac_f32_e32 v129, v86, v86
	v_add_f32_e32 v128, v128, v129
	v_mul_f32_e32 v129, v97, v97
	v_fmac_f32_e32 v129, v96, v96
	v_add_f32_e32 v128, v129, v128
	v_mul_f32_e32 v129, v99, v99
	v_fmac_f32_e32 v129, v98, v98
	v_add_f32_e32 v128, v129, v128
	v_mov_b32_e32 v129, v128
	s_nop 1
	v_permlane16_swap_b32_e32 v128, v129
	v_add_f32_e32 v128, v128, v129
	v_mov_b32_e32 v129, v128
	s_nop 1
	v_permlane32_swap_b32_e32 v128, v129
	s_and_saveexec_b64 s[4:5], s[0:1]
	v_add_f32_e32 v128, v128, v129
	ds_write_b32 v172, v128
	s_or_b64 exec, exec, s[4:5]
	v_mul_f32_e32 v128, v77, v77
	v_mul_f32_e32 v129, v79, v79
	v_fmac_f32_e32 v128, v76, v76
	v_fmac_f32_e32 v129, v78, v78
	v_add_f32_e32 v128, v128, v129
	v_mul_f32_e32 v129, v89, v89
	v_fmac_f32_e32 v129, v88, v88
	v_add_f32_e32 v128, v129, v128
	v_mul_f32_e32 v129, v91, v91
	v_fmac_f32_e32 v129, v90, v90
	v_add_f32_e32 v128, v129, v128
	v_mov_b32_e32 v129, v128
	s_nop 1
	v_permlane16_swap_b32_e32 v128, v129
	v_add_f32_e32 v128, v128, v129
	v_mov_b32_e32 v129, v128
	s_nop 1
	v_permlane32_swap_b32_e32 v128, v129
	s_and_saveexec_b64 s[4:5], s[0:1]
	v_add_f32_e32 v128, v128, v129
	ds_write_b32 v172, v128 offset:16
	s_or_b64 exec, exec, s[4:5]
	v_mul_f32_e32 v128, v69, v69
	v_mul_f32_e32 v129, v71, v71
	v_fmac_f32_e32 v128, v68, v68
	v_fmac_f32_e32 v129, v70, v70
	v_add_f32_e32 v128, v128, v129
	v_mul_f32_e32 v129, v81, v81
	v_fmac_f32_e32 v129, v80, v80
	v_add_f32_e32 v128, v129, v128
	v_mul_f32_e32 v129, v83, v83
	v_fmac_f32_e32 v129, v82, v82
	v_add_f32_e32 v128, v129, v128
	v_mov_b32_e32 v129, v128
	s_nop 1
	v_permlane16_swap_b32_e32 v128, v129
	v_add_f32_e32 v128, v128, v129
	v_mov_b32_e32 v129, v128
	s_nop 1
	v_permlane32_swap_b32_e32 v128, v129
	s_and_saveexec_b64 s[4:5], s[0:1]
	v_add_f32_e32 v128, v128, v129
	ds_write_b32 v173, v128
	s_or_b64 exec, exec, s[4:5]
	v_mul_f32_e32 v128, v61, v61
	v_mul_f32_e32 v129, v63, v63
	v_fmac_f32_e32 v128, v60, v60
	v_fmac_f32_e32 v129, v62, v62
	v_add_f32_e32 v128, v128, v129
	v_mul_f32_e32 v129, v73, v73
	v_fmac_f32_e32 v129, v72, v72
	v_add_f32_e32 v128, v129, v128
	v_mul_f32_e32 v129, v75, v75
	v_fmac_f32_e32 v129, v74, v74
	v_add_f32_e32 v128, v129, v128
	v_mov_b32_e32 v129, v128
	s_nop 1
	v_permlane16_swap_b32_e32 v128, v129
	v_add_f32_e32 v128, v128, v129
	v_mov_b32_e32 v129, v128
	s_nop 1
	v_permlane32_swap_b32_e32 v128, v129
	s_and_saveexec_b64 s[4:5], s[0:1]
	v_add_f32_e32 v128, v128, v129
	ds_write_b32 v173, v128 offset:16
	s_or_b64 exec, exec, s[4:5]
	v_mul_f32_e32 v128, v53, v53
	v_mul_f32_e32 v129, v55, v55
	v_fmac_f32_e32 v128, v52, v52
	v_fmac_f32_e32 v129, v54, v54
	v_add_f32_e32 v128, v128, v129
	v_mul_f32_e32 v129, v65, v65
	v_fmac_f32_e32 v129, v64, v64
	v_add_f32_e32 v128, v129, v128
	v_mul_f32_e32 v129, v67, v67
	v_fmac_f32_e32 v129, v66, v66
	v_add_f32_e32 v128, v129, v128
	v_mov_b32_e32 v129, v128
	s_nop 1
	v_permlane16_swap_b32_e32 v128, v129
	v_add_f32_e32 v128, v128, v129
	v_mov_b32_e32 v129, v128
	s_nop 1
	v_permlane32_swap_b32_e32 v128, v129
	s_and_saveexec_b64 s[4:5], s[0:1]
	v_add_f32_e32 v128, v128, v129
	ds_write_b32 v174, v128
	s_or_b64 exec, exec, s[4:5]
	v_mul_f32_e32 v128, v45, v45
	v_mul_f32_e32 v129, v47, v47
	v_fmac_f32_e32 v128, v44, v44
	v_fmac_f32_e32 v129, v46, v46
	v_add_f32_e32 v128, v128, v129
	v_mul_f32_e32 v129, v57, v57
	v_fmac_f32_e32 v129, v56, v56
	v_add_f32_e32 v128, v129, v128
	v_mul_f32_e32 v129, v59, v59
	v_fmac_f32_e32 v129, v58, v58
	v_add_f32_e32 v128, v129, v128
	v_mov_b32_e32 v129, v128
	s_nop 1
	v_permlane16_swap_b32_e32 v128, v129
	v_add_f32_e32 v128, v128, v129
	v_mov_b32_e32 v129, v128
	s_nop 1
	v_permlane32_swap_b32_e32 v128, v129
	s_and_saveexec_b64 s[4:5], s[0:1]
	v_add_f32_e32 v128, v128, v129
	ds_write_b32 v174, v128 offset:16
	s_or_b64 exec, exec, s[4:5]
	v_mul_f32_e32 v128, v37, v37
	v_mul_f32_e32 v129, v39, v39
	v_fmac_f32_e32 v128, v36, v36
	v_fmac_f32_e32 v129, v38, v38
	v_add_f32_e32 v128, v128, v129
	v_mul_f32_e32 v129, v49, v49
	v_fmac_f32_e32 v129, v48, v48
	v_add_f32_e32 v128, v129, v128
	v_mul_f32_e32 v129, v51, v51
	v_fmac_f32_e32 v129, v50, v50
	v_add_f32_e32 v128, v129, v128
	v_mov_b32_e32 v129, v128
	s_nop 1
	v_permlane16_swap_b32_e32 v128, v129
	v_add_f32_e32 v128, v128, v129
	v_mov_b32_e32 v129, v128
	s_nop 1
	v_permlane32_swap_b32_e32 v128, v129
	s_and_saveexec_b64 s[4:5], s[0:1]
	v_add_f32_e32 v128, v128, v129
	ds_write_b32 v175, v128
	s_or_b64 exec, exec, s[4:5]
	v_mul_f32_e32 v128, v29, v29
	v_mul_f32_e32 v129, v31, v31
	v_fmac_f32_e32 v128, v28, v28
	v_fmac_f32_e32 v129, v30, v30
	v_add_f32_e32 v128, v128, v129
	v_mul_f32_e32 v129, v41, v41
	v_fmac_f32_e32 v129, v40, v40
	v_add_f32_e32 v128, v129, v128
	v_mul_f32_e32 v129, v43, v43
	v_fmac_f32_e32 v129, v42, v42
	v_add_f32_e32 v128, v129, v128
	v_mov_b32_e32 v129, v128
	s_nop 1
	v_permlane16_swap_b32_e32 v128, v129
	v_add_f32_e32 v128, v128, v129
	v_mov_b32_e32 v129, v128
	s_nop 1
	v_permlane32_swap_b32_e32 v128, v129
	s_and_saveexec_b64 s[4:5], s[0:1]
	v_add_f32_e32 v128, v128, v129
	ds_write_b32 v175, v128 offset:16
	s_or_b64 exec, exec, s[4:5]
	v_mul_f32_e32 v128, v21, v21
	v_mul_f32_e32 v129, v23, v23
	v_fmac_f32_e32 v128, v20, v20
	v_fmac_f32_e32 v129, v22, v22
	v_add_f32_e32 v128, v128, v129
	v_mul_f32_e32 v129, v33, v33
	v_fmac_f32_e32 v129, v32, v32
	v_add_f32_e32 v128, v129, v128
	v_mul_f32_e32 v129, v35, v35
	v_fmac_f32_e32 v129, v34, v34
	v_add_f32_e32 v128, v129, v128
	v_mov_b32_e32 v129, v128
	s_nop 1
	v_permlane16_swap_b32_e32 v128, v129
	v_add_f32_e32 v128, v128, v129
	v_mov_b32_e32 v129, v128
	s_nop 1
	v_permlane32_swap_b32_e32 v128, v129
	s_and_saveexec_b64 s[4:5], s[0:1]
	v_add_f32_e32 v128, v128, v129
	ds_write_b32 v176, v128
	s_or_b64 exec, exec, s[4:5]
	v_mul_f32_e32 v128, v17, v17
	v_mul_f32_e32 v129, v19, v19
	v_fmac_f32_e32 v128, v16, v16
	v_fmac_f32_e32 v129, v18, v18
	v_add_f32_e32 v128, v128, v129
	v_mul_f32_e32 v129, v25, v25
	v_fmac_f32_e32 v129, v24, v24
	v_add_f32_e32 v128, v129, v128
	v_mul_f32_e32 v129, v27, v27
	v_fmac_f32_e32 v129, v26, v26
	v_add_f32_e32 v128, v129, v128
	v_mov_b32_e32 v129, v128
	s_nop 1
	v_permlane16_swap_b32_e32 v128, v129
	v_add_f32_e32 v128, v128, v129
	v_mov_b32_e32 v129, v128
	s_nop 1
	v_permlane32_swap_b32_e32 v128, v129
	s_and_saveexec_b64 s[4:5], s[0:1]
	v_add_f32_e32 v128, v128, v129
	ds_write_b32 v176, v128 offset:16
	s_or_b64 exec, exec, s[4:5]
	v_mul_f32_e32 v128, v9, v9
	v_mul_f32_e32 v129, v11, v11
	v_fmac_f32_e32 v128, v8, v8
	v_fmac_f32_e32 v129, v10, v10
	v_add_f32_e32 v128, v128, v129
	v_mul_f32_e32 v129, v13, v13
	v_fmac_f32_e32 v129, v12, v12
	v_add_f32_e32 v128, v129, v128
	v_mul_f32_e32 v129, v15, v15
	v_fmac_f32_e32 v129, v14, v14
	v_add_f32_e32 v128, v129, v128
	v_mov_b32_e32 v129, v128
	s_nop 1
	v_permlane16_swap_b32_e32 v128, v129
	v_add_f32_e32 v128, v128, v129
	v_mov_b32_e32 v129, v128
	s_nop 1
	v_permlane32_swap_b32_e32 v128, v129
	s_and_saveexec_b64 s[4:5], s[0:1]
	v_add_f32_e32 v128, v128, v129
	ds_write_b32 v177, v128
	s_or_b64 exec, exec, s[4:5]
	v_mul_f32_e32 v128, v1, v1
	v_mul_f32_e32 v129, v3, v3
	v_fmac_f32_e32 v128, v0, v0
	v_fmac_f32_e32 v129, v2, v2
	v_add_f32_e32 v128, v128, v129
	v_mul_f32_e32 v129, v5, v5
	v_fmac_f32_e32 v129, v4, v4
	v_add_f32_e32 v128, v129, v128
	v_mul_f32_e32 v129, v7, v7
	v_fmac_f32_e32 v129, v6, v6
	v_add_f32_e32 v128, v129, v128
	v_mov_b32_e32 v129, v128
	s_nop 1
	v_permlane16_swap_b32_e32 v128, v129
	v_add_f32_e32 v128, v128, v129
	v_mov_b32_e32 v129, v128
	s_nop 1
	v_permlane32_swap_b32_e32 v128, v129
	s_and_saveexec_b64 s[4:5], s[0:1]
	v_add_f32_e32 v128, v128, v129
	ds_write_b32 v177, v128 offset:16
	s_or_b64 exec, exec, s[4:5]
	s_lshl_b32 s17, s43, 2
	v_readlane_b32 s72, v254, 0
	s_cmp_lt_u32 s24, 8
	v_readlane_b32 s84, v254, 12
	v_readlane_b32 s85, v254, 13
	s_cselect_b64 vcc, -1, 0
	v_readlane_b32 s86, v254, 14
	v_readlane_b32 s87, v254, 15
	s_mov_b64 s[28:29], s[84:85]
	s_and_b64 s[4:5], vcc, exec
	v_readlane_b32 s52, v254, 16
	s_mov_b64 s[30:31], s[86:87]
	v_readlane_b32 s53, v254, 17
	s_cselect_b32 s4, s30, s52
	s_cselect_b32 s5, s31, s53
	s_cselect_b32 s23, s51, 0xe000000
	s_add_u32 s4, s4, s17
	s_waitcnt lgkmcnt(0)
	s_barrier
	s_addc_u32 s5, s5, 0
	v_lshlrev_b32_e32 v128, 2, v146
	global_load_dwordx4 v[132:135], v128, s[4:5]
	s_nop 0
	global_load_dwordx4 v[128:131], v128, s[4:5] offset:16
	ds_read_b128 v[188:191], v169
	v_cndmask_b32_e32 v156, 1.0, v180, vcc
	v_readlane_b32 s58, v254, 22
	v_readlane_b32 s59, v254, 23
	s_add_u32 s5, s58, s23
	s_waitcnt lgkmcnt(0)
	v_mov_b32_e32 v154, v189
	v_mov_b32_e32 v155, v190
	v_mov_b32_e32 v189, v191
	v_pk_add_f32 v[154:155], v[154:155], v[188:189]
	s_addc_u32 s17, s59, 0
	v_add_f32_e32 v154, v154, v155
	v_fmamk_f32 v154, v154, 0x3c000000, v179
	v_rsq_f32_e32 v155, v154
	s_lshl_b32 s4, s22, 8
	s_lshl_b32 s15, s15, 1
	s_add_u32 s5, s5, s15
	v_mul_f32_e32 v158, v156, v155
	v_pk_mul_f32 v[124:125], v[124:125], v[158:159] op_sel_hi:[1,0]
	v_pk_mul_f32 v[120:121], v[120:121], v[158:159] op_sel_hi:[1,0]
	v_pk_mul_f32 v[122:123], v[122:123], v[158:159] op_sel_hi:[1,0]
	v_pk_mul_f32 v[126:127], v[126:127], v[158:159] op_sel_hi:[1,0]
	v_add_u32_e32 v154, s4, v147
	s_addc_u32 s15, s17, 0
	s_lshl_b32 s17, s43, 1
	v_ashrrev_i32_e32 v155, 31, v154
	s_add_u32 s22, s5, s17
	v_lshlrev_b32_e32 v144, 1, v146
	s_addc_u32 s23, s15, 0
	v_readlane_b32 s54, v254, 18
	v_readlane_b32 s55, v254, 19
	v_readlane_b32 s56, v254, 20
	v_readlane_b32 s57, v254, 21
	v_readlane_b32 s73, v254, 1
	v_readlane_b32 s74, v254, 2
	v_readlane_b32 s75, v254, 3
	v_readlane_b32 s76, v254, 4
	v_readlane_b32 s77, v254, 5
	v_readlane_b32 s78, v254, 6
	v_readlane_b32 s79, v254, 7
	v_readlane_b32 s80, v254, 8
	v_readlane_b32 s81, v254, 9
	v_readlane_b32 s82, v254, 10
	v_readlane_b32 s83, v254, 11
	s_waitcnt vmcnt(0)
	v_pk_mul_f32 v[158:159], v[134:135], v[122:123]
	v_pk_mul_f32 v[124:125], v[128:129], v[124:125]
	v_pk_mul_f32 v[120:121], v[132:133], v[120:121]
	v_pk_mul_f32 v[126:127], v[130:131], v[126:127]
	v_cvt_pk_bf16_f32 v122, v120, v121
	v_cvt_pk_bf16_f32 v123, v158, v159
	v_cvt_pk_bf16_f32 v124, v124, v125
	s_nop 0
	v_cvt_pk_bf16_f32 v125, v126, v127
	ds_read_b128 v[188:191], v169 offset:16
	v_lshlrev_b64 v[126:127], 12, v[154:155]
	s_waitcnt lgkmcnt(0)
	v_mov_b32_e32 v120, v189
	v_mov_b32_e32 v121, v190
	v_mov_b32_e32 v189, v191
	v_pk_add_f32 v[120:121], v[120:121], v[188:189]
	s_nop 0
	v_add_f32_e32 v120, v120, v121
	v_fmamk_f32 v120, v120, 0x3c000000, v179
	v_rsq_f32_e32 v154, v120
	v_lshl_add_u64 v[120:121], s[22:23], 0, v[144:145]
	v_lshl_add_u64 v[126:127], v[120:121], 0, v[126:127]
	global_store_dwordx4 v[126:127], v[122:125], off nt
	s_nop 1
	v_mul_f32_e32 v122, v156, v154
	v_pk_mul_f32 v[108:109], v[108:109], v[122:123] op_sel_hi:[1,0]
	v_pk_mul_f32 v[110:111], v[110:111], v[122:123] op_sel_hi:[1,0]
	v_pk_mul_f32 v[116:117], v[116:117], v[122:123] op_sel_hi:[1,0]
	v_pk_mul_f32 v[118:119], v[118:119], v[122:123] op_sel_hi:[1,0]
	v_pk_mul_f32 v[110:111], v[134:135], v[110:111]
	v_pk_mul_f32 v[108:109], v[132:133], v[108:109]
	v_pk_mul_f32 v[118:119], v[130:131], v[118:119]
	v_pk_mul_f32 v[116:117], v[128:129], v[116:117]
	v_cvt_pk_bf16_f32 v108, v108, v109
	v_cvt_pk_bf16_f32 v109, v110, v111
	s_nop 0
	v_cvt_pk_bf16_f32 v110, v116, v117
	v_cvt_pk_bf16_f32 v111, v118, v119
	ds_read_b128 v[116:119], v181
	global_store_dwordx4 v[126:127], v[108:111], off offset:256 nt
	s_waitcnt lgkmcnt(0)
	v_mov_b32_e32 v122, v117
	v_mov_b32_e32 v123, v118
	v_mov_b32_e32 v117, v119
	v_pk_add_f32 v[116:117], v[122:123], v[116:117]
	s_nop 0
	v_add_f32_e32 v116, v116, v117
	v_fmamk_f32 v116, v116, 0x3c000000, v179
	v_rsq_f32_e32 v116, v116
	s_nop 0
	v_mul_f32_e32 v108, v156, v116
	v_pk_mul_f32 v[100:101], v[100:101], v[108:109] op_sel_hi:[1,0]
	v_pk_mul_f32 v[102:103], v[102:103], v[108:109] op_sel_hi:[1,0]
	v_pk_mul_f32 v[110:111], v[112:113], v[108:109] op_sel_hi:[1,0]
	v_pk_mul_f32 v[108:109], v[114:115], v[108:109] op_sel_hi:[1,0]
	v_pk_mul_f32 v[102:103], v[134:135], v[102:103]
	v_pk_mul_f32 v[100:101], v[132:133], v[100:101]
	v_pk_mul_f32 v[108:109], v[130:131], v[108:109]
	v_pk_mul_f32 v[110:111], v[128:129], v[110:111]
	v_cvt_pk_bf16_f32 v100, v100, v101
	v_cvt_pk_bf16_f32 v101, v102, v103
	v_add_u32_e32 v112, s4, v162
	v_cvt_pk_bf16_f32 v102, v110, v111
	v_cvt_pk_bf16_f32 v103, v108, v109
	ds_read_b128 v[108:111], v181 offset:16
	v_ashrrev_i32_e32 v113, 31, v112
	s_waitcnt lgkmcnt(0)
	v_mov_b32_e32 v114, v109
	v_mov_b32_e32 v115, v110
	v_mov_b32_e32 v109, v111
	v_pk_add_f32 v[108:109], v[114:115], v[108:109]
	s_nop 0
	v_add_f32_e32 v108, v108, v109
	v_fmamk_f32 v108, v108, 0x3c000000, v179
	v_rsq_f32_e32 v110, v108
	v_lshlrev_b64 v[108:109], 12, v[112:113]
	v_lshl_add_u64 v[108:109], v[120:121], 0, v[108:109]
	global_store_dwordx4 v[108:109], v[100:103], off nt
	s_nop 1
	v_mul_f32_e32 v100, v156, v110
	v_pk_mul_f32 v[92:93], v[92:93], v[100:101] op_sel_hi:[1,0]
	v_pk_mul_f32 v[94:95], v[94:95], v[100:101] op_sel_hi:[1,0]
	v_pk_mul_f32 v[102:103], v[104:105], v[100:101] op_sel_hi:[1,0]
	v_pk_mul_f32 v[100:101], v[106:107], v[100:101] op_sel_hi:[1,0]
	v_pk_mul_f32 v[94:95], v[134:135], v[94:95]
	v_pk_mul_f32 v[92:93], v[132:133], v[92:93]
	v_pk_mul_f32 v[100:101], v[130:131], v[100:101]
	v_pk_mul_f32 v[102:103], v[128:129], v[102:103]
	v_cvt_pk_bf16_f32 v92, v92, v93
	v_cvt_pk_bf16_f32 v93, v94, v95
	s_nop 0
	v_cvt_pk_bf16_f32 v94, v102, v103
	v_cvt_pk_bf16_f32 v95, v100, v101
	ds_read_b128 v[100:103], v182
	global_store_dwordx4 v[108:109], v[92:95], off offset:256 nt
	s_waitcnt lgkmcnt(0)
	v_mov_b32_e32 v104, v101
	v_mov_b32_e32 v105, v102
	v_mov_b32_e32 v101, v103
	v_pk_add_f32 v[100:101], v[104:105], v[100:101]
	s_nop 0
	v_add_f32_e32 v100, v100, v101
	v_fmamk_f32 v100, v100, 0x3c000000, v179
	v_rsq_f32_e32 v100, v100
	s_nop 0
	v_mul_f32_e32 v92, v156, v100
	v_pk_mul_f32 v[84:85], v[84:85], v[92:93] op_sel_hi:[1,0]
	v_pk_mul_f32 v[86:87], v[86:87], v[92:93] op_sel_hi:[1,0]
	v_pk_mul_f32 v[94:95], v[96:97], v[92:93] op_sel_hi:[1,0]
	v_pk_mul_f32 v[92:93], v[98:99], v[92:93] op_sel_hi:[1,0]
	v_pk_mul_f32 v[86:87], v[134:135], v[86:87]
	v_pk_mul_f32 v[84:85], v[132:133], v[84:85]
	v_pk_mul_f32 v[92:93], v[130:131], v[92:93]
	v_pk_mul_f32 v[94:95], v[128:129], v[94:95]
	v_cvt_pk_bf16_f32 v84, v84, v85
	v_cvt_pk_bf16_f32 v85, v86, v87
	v_add_u32_e32 v96, s4, v163
	v_cvt_pk_bf16_f32 v86, v94, v95
	v_cvt_pk_bf16_f32 v87, v92, v93
	ds_read_b128 v[92:95], v182 offset:16
	v_ashrrev_i32_e32 v97, 31, v96
	s_waitcnt lgkmcnt(0)
	v_mov_b32_e32 v98, v93
	v_mov_b32_e32 v99, v94
	v_mov_b32_e32 v93, v95
	v_pk_add_f32 v[92:93], v[98:99], v[92:93]
	s_nop 0
	v_add_f32_e32 v92, v92, v93
	v_fmamk_f32 v92, v92, 0x3c000000, v179
	v_rsq_f32_e32 v94, v92
	v_lshlrev_b64 v[92:93], 12, v[96:97]
	v_lshl_add_u64 v[92:93], v[120:121], 0, v[92:93]
	global_store_dwordx4 v[92:93], v[84:87], off nt
	s_nop 1
	v_mul_f32_e32 v84, v156, v94
	v_pk_mul_f32 v[76:77], v[76:77], v[84:85] op_sel_hi:[1,0]
	v_pk_mul_f32 v[78:79], v[78:79], v[84:85] op_sel_hi:[1,0]
	v_pk_mul_f32 v[86:87], v[88:89], v[84:85] op_sel_hi:[1,0]
	v_pk_mul_f32 v[84:85], v[90:91], v[84:85] op_sel_hi:[1,0]
	v_pk_mul_f32 v[78:79], v[134:135], v[78:79]
	v_pk_mul_f32 v[76:77], v[132:133], v[76:77]
	v_pk_mul_f32 v[84:85], v[130:131], v[84:85]
	v_pk_mul_f32 v[86:87], v[128:129], v[86:87]
	v_cvt_pk_bf16_f32 v76, v76, v77
	v_cvt_pk_bf16_f32 v77, v78, v79
	s_nop 0
	v_cvt_pk_bf16_f32 v78, v86, v87
	v_cvt_pk_bf16_f32 v79, v84, v85
	ds_read_b128 v[84:87], v183
	global_store_dwordx4 v[92:93], v[76:79], off offset:256 nt
	s_waitcnt lgkmcnt(0)
	v_mov_b32_e32 v88, v85
	v_mov_b32_e32 v89, v86
	v_mov_b32_e32 v85, v87
	v_pk_add_f32 v[84:85], v[88:89], v[84:85]
	s_nop 0
	v_add_f32_e32 v84, v84, v85
	v_fmamk_f32 v84, v84, 0x3c000000, v179
	v_rsq_f32_e32 v84, v84
	s_nop 0
	v_mul_f32_e32 v76, v156, v84
	v_pk_mul_f32 v[68:69], v[68:69], v[76:77] op_sel_hi:[1,0]
	v_pk_mul_f32 v[70:71], v[70:71], v[76:77] op_sel_hi:[1,0]
	v_pk_mul_f32 v[78:79], v[80:81], v[76:77] op_sel_hi:[1,0]
	v_pk_mul_f32 v[76:77], v[82:83], v[76:77] op_sel_hi:[1,0]
	v_pk_mul_f32 v[70:71], v[134:135], v[70:71]
	v_pk_mul_f32 v[68:69], v[132:133], v[68:69]
	v_pk_mul_f32 v[76:77], v[130:131], v[76:77]
	v_pk_mul_f32 v[78:79], v[128:129], v[78:79]
	v_cvt_pk_bf16_f32 v68, v68, v69
	v_cvt_pk_bf16_f32 v69, v70, v71
	v_add_u32_e32 v80, s4, v164
	v_cvt_pk_bf16_f32 v70, v78, v79
	v_cvt_pk_bf16_f32 v71, v76, v77
	ds_read_b128 v[76:79], v183 offset:16
	v_ashrrev_i32_e32 v81, 31, v80
	s_waitcnt lgkmcnt(0)
	v_mov_b32_e32 v82, v77
	v_mov_b32_e32 v83, v78
	v_mov_b32_e32 v77, v79
	v_pk_add_f32 v[76:77], v[82:83], v[76:77]
	s_nop 0
	v_add_f32_e32 v76, v76, v77
	v_fmamk_f32 v76, v76, 0x3c000000, v179
	v_rsq_f32_e32 v78, v76
	v_lshlrev_b64 v[76:77], 12, v[80:81]
	v_lshl_add_u64 v[76:77], v[120:121], 0, v[76:77]
	global_store_dwordx4 v[76:77], v[68:71], off nt
	s_nop 1
	v_mul_f32_e32 v68, v156, v78
	v_pk_mul_f32 v[60:61], v[60:61], v[68:69] op_sel_hi:[1,0]
	v_pk_mul_f32 v[62:63], v[62:63], v[68:69] op_sel_hi:[1,0]
	v_pk_mul_f32 v[70:71], v[72:73], v[68:69] op_sel_hi:[1,0]
	v_pk_mul_f32 v[68:69], v[74:75], v[68:69] op_sel_hi:[1,0]
	v_pk_mul_f32 v[62:63], v[134:135], v[62:63]
	v_pk_mul_f32 v[60:61], v[132:133], v[60:61]
	v_pk_mul_f32 v[68:69], v[130:131], v[68:69]
	v_pk_mul_f32 v[70:71], v[128:129], v[70:71]
	v_cvt_pk_bf16_f32 v60, v60, v61
	v_cvt_pk_bf16_f32 v61, v62, v63
	s_nop 0
	v_cvt_pk_bf16_f32 v62, v70, v71
	v_cvt_pk_bf16_f32 v63, v68, v69
	ds_read_b128 v[68:71], v184
	global_store_dwordx4 v[76:77], v[60:63], off offset:256 nt
	s_waitcnt lgkmcnt(0)
	v_mov_b32_e32 v72, v69
	v_mov_b32_e32 v73, v70
	v_mov_b32_e32 v69, v71
	v_pk_add_f32 v[68:69], v[72:73], v[68:69]
	s_nop 0
	v_add_f32_e32 v68, v68, v69
	v_fmamk_f32 v68, v68, 0x3c000000, v179
	v_rsq_f32_e32 v68, v68
	s_nop 0
	v_mul_f32_e32 v60, v156, v68
	v_pk_mul_f32 v[52:53], v[52:53], v[60:61] op_sel_hi:[1,0]
	v_pk_mul_f32 v[54:55], v[54:55], v[60:61] op_sel_hi:[1,0]
	v_pk_mul_f32 v[62:63], v[64:65], v[60:61] op_sel_hi:[1,0]
	v_pk_mul_f32 v[60:61], v[66:67], v[60:61] op_sel_hi:[1,0]
	v_pk_mul_f32 v[54:55], v[134:135], v[54:55]
	v_pk_mul_f32 v[52:53], v[132:133], v[52:53]
	v_pk_mul_f32 v[60:61], v[130:131], v[60:61]
	v_pk_mul_f32 v[62:63], v[128:129], v[62:63]
	v_cvt_pk_bf16_f32 v52, v52, v53
	v_cvt_pk_bf16_f32 v53, v54, v55
	v_add_u32_e32 v64, s4, v165
	v_cvt_pk_bf16_f32 v54, v62, v63
	v_cvt_pk_bf16_f32 v55, v60, v61
	ds_read_b128 v[60:63], v184 offset:16
	v_ashrrev_i32_e32 v65, 31, v64
	s_waitcnt lgkmcnt(0)
	v_mov_b32_e32 v66, v61
	v_mov_b32_e32 v67, v62
	v_mov_b32_e32 v61, v63
	v_pk_add_f32 v[60:61], v[66:67], v[60:61]
	s_nop 0
	v_add_f32_e32 v60, v60, v61
	v_fmamk_f32 v60, v60, 0x3c000000, v179
	v_rsq_f32_e32 v62, v60
	v_lshlrev_b64 v[60:61], 12, v[64:65]
	v_lshl_add_u64 v[60:61], v[120:121], 0, v[60:61]
	global_store_dwordx4 v[60:61], v[52:55], off nt
	s_nop 1
	v_mul_f32_e32 v52, v156, v62
	v_pk_mul_f32 v[44:45], v[44:45], v[52:53] op_sel_hi:[1,0]
	v_pk_mul_f32 v[46:47], v[46:47], v[52:53] op_sel_hi:[1,0]
	v_pk_mul_f32 v[54:55], v[56:57], v[52:53] op_sel_hi:[1,0]
	v_pk_mul_f32 v[52:53], v[58:59], v[52:53] op_sel_hi:[1,0]
	v_pk_mul_f32 v[46:47], v[134:135], v[46:47]
	v_pk_mul_f32 v[44:45], v[132:133], v[44:45]
	v_pk_mul_f32 v[52:53], v[130:131], v[52:53]
	v_pk_mul_f32 v[54:55], v[128:129], v[54:55]
	v_cvt_pk_bf16_f32 v44, v44, v45
	v_cvt_pk_bf16_f32 v45, v46, v47
	s_nop 0
	v_cvt_pk_bf16_f32 v46, v54, v55
	v_cvt_pk_bf16_f32 v47, v52, v53
	ds_read_b128 v[52:55], v185
	global_store_dwordx4 v[60:61], v[44:47], off offset:256 nt
	s_waitcnt lgkmcnt(0)
	v_mov_b32_e32 v56, v53
	v_mov_b32_e32 v57, v54
	v_mov_b32_e32 v53, v55
	v_pk_add_f32 v[52:53], v[56:57], v[52:53]
	s_nop 0
	v_add_f32_e32 v52, v52, v53
	v_fmamk_f32 v52, v52, 0x3c000000, v179
	v_rsq_f32_e32 v52, v52
	s_nop 0
	v_mul_f32_e32 v44, v156, v52
	v_pk_mul_f32 v[36:37], v[36:37], v[44:45] op_sel_hi:[1,0]
	v_pk_mul_f32 v[38:39], v[38:39], v[44:45] op_sel_hi:[1,0]
	v_pk_mul_f32 v[46:47], v[48:49], v[44:45] op_sel_hi:[1,0]
	v_pk_mul_f32 v[44:45], v[50:51], v[44:45] op_sel_hi:[1,0]
	v_pk_mul_f32 v[38:39], v[134:135], v[38:39]
	v_pk_mul_f32 v[36:37], v[132:133], v[36:37]
	v_pk_mul_f32 v[44:45], v[130:131], v[44:45]
	v_pk_mul_f32 v[46:47], v[128:129], v[46:47]
	v_cvt_pk_bf16_f32 v36, v36, v37
	v_cvt_pk_bf16_f32 v37, v38, v39
	v_add_u32_e32 v48, s4, v166
	v_cvt_pk_bf16_f32 v38, v46, v47
	v_cvt_pk_bf16_f32 v39, v44, v45
	ds_read_b128 v[44:47], v185 offset:16
	v_ashrrev_i32_e32 v49, 31, v48
	s_waitcnt lgkmcnt(0)
	v_mov_b32_e32 v50, v45
	v_mov_b32_e32 v51, v46
	v_mov_b32_e32 v45, v47
	v_pk_add_f32 v[44:45], v[50:51], v[44:45]
	s_nop 0
	v_add_f32_e32 v44, v44, v45
	v_fmamk_f32 v44, v44, 0x3c000000, v179
	v_rsq_f32_e32 v46, v44
	v_lshlrev_b64 v[44:45], 12, v[48:49]
	v_lshl_add_u64 v[44:45], v[120:121], 0, v[44:45]
	global_store_dwordx4 v[44:45], v[36:39], off nt
	s_nop 1
	v_mul_f32_e32 v36, v156, v46
	v_pk_mul_f32 v[28:29], v[28:29], v[36:37] op_sel_hi:[1,0]
	v_pk_mul_f32 v[30:31], v[30:31], v[36:37] op_sel_hi:[1,0]
	v_pk_mul_f32 v[38:39], v[40:41], v[36:37] op_sel_hi:[1,0]
	v_pk_mul_f32 v[36:37], v[42:43], v[36:37] op_sel_hi:[1,0]
	v_pk_mul_f32 v[30:31], v[134:135], v[30:31]
	v_pk_mul_f32 v[28:29], v[132:133], v[28:29]
	v_pk_mul_f32 v[36:37], v[130:131], v[36:37]
	v_pk_mul_f32 v[38:39], v[128:129], v[38:39]
	v_cvt_pk_bf16_f32 v28, v28, v29
	v_cvt_pk_bf16_f32 v29, v30, v31
	s_nop 0
	v_cvt_pk_bf16_f32 v30, v38, v39
	v_cvt_pk_bf16_f32 v31, v36, v37
	ds_read_b128 v[36:39], v186
	global_store_dwordx4 v[44:45], v[28:31], off offset:256 nt
	s_waitcnt lgkmcnt(0)
	v_mov_b32_e32 v40, v37
	v_mov_b32_e32 v41, v38
	v_mov_b32_e32 v37, v39
	v_pk_add_f32 v[36:37], v[40:41], v[36:37]
	s_nop 0
	v_add_f32_e32 v36, v36, v37
	v_fmamk_f32 v36, v36, 0x3c000000, v179
	v_rsq_f32_e32 v36, v36
	s_nop 0
	v_mul_f32_e32 v28, v156, v36
	v_pk_mul_f32 v[20:21], v[20:21], v[28:29] op_sel_hi:[1,0]
	v_pk_mul_f32 v[22:23], v[22:23], v[28:29] op_sel_hi:[1,0]
	v_pk_mul_f32 v[30:31], v[32:33], v[28:29] op_sel_hi:[1,0]
	v_pk_mul_f32 v[28:29], v[34:35], v[28:29] op_sel_hi:[1,0]
	v_pk_mul_f32 v[22:23], v[134:135], v[22:23]
	v_pk_mul_f32 v[20:21], v[132:133], v[20:21]
	v_pk_mul_f32 v[28:29], v[130:131], v[28:29]
	v_pk_mul_f32 v[30:31], v[128:129], v[30:31]
	v_cvt_pk_bf16_f32 v20, v20, v21
	v_cvt_pk_bf16_f32 v21, v22, v23
	v_add_u32_e32 v32, s4, v167
	v_cvt_pk_bf16_f32 v22, v30, v31
	v_cvt_pk_bf16_f32 v23, v28, v29
	ds_read_b128 v[28:31], v186 offset:16
	v_ashrrev_i32_e32 v33, 31, v32
	s_waitcnt lgkmcnt(0)
	v_mov_b32_e32 v34, v29
	v_mov_b32_e32 v35, v30
	v_mov_b32_e32 v29, v31
	v_pk_add_f32 v[28:29], v[34:35], v[28:29]
	s_nop 0
	v_add_f32_e32 v28, v28, v29
	v_fmamk_f32 v28, v28, 0x3c000000, v179
	v_rsq_f32_e32 v30, v28
	v_lshlrev_b64 v[28:29], 12, v[32:33]
	v_lshl_add_u64 v[28:29], v[120:121], 0, v[28:29]
	global_store_dwordx4 v[28:29], v[20:23], off nt
	s_nop 1
	v_mul_f32_e32 v20, v156, v30
	v_pk_mul_f32 v[16:17], v[16:17], v[20:21] op_sel_hi:[1,0]
	v_pk_mul_f32 v[18:19], v[18:19], v[20:21] op_sel_hi:[1,0]
	v_pk_mul_f32 v[22:23], v[24:25], v[20:21] op_sel_hi:[1,0]
	v_pk_mul_f32 v[20:21], v[26:27], v[20:21] op_sel_hi:[1,0]
	v_pk_mul_f32 v[18:19], v[134:135], v[18:19]
	v_pk_mul_f32 v[16:17], v[132:133], v[16:17]
	v_pk_mul_f32 v[20:21], v[130:131], v[20:21]
	v_pk_mul_f32 v[22:23], v[128:129], v[22:23]
	v_cvt_pk_bf16_f32 v16, v16, v17
	v_cvt_pk_bf16_f32 v17, v18, v19
	s_nop 0
	v_cvt_pk_bf16_f32 v18, v22, v23
	v_cvt_pk_bf16_f32 v19, v20, v21
	ds_read_b128 v[20:23], v187
	global_store_dwordx4 v[28:29], v[16:19], off offset:256 nt
	s_waitcnt lgkmcnt(0)
	v_mov_b32_e32 v24, v21
	v_mov_b32_e32 v25, v22
	v_mov_b32_e32 v21, v23
	v_pk_add_f32 v[20:21], v[24:25], v[20:21]
	s_nop 0
	v_add_f32_e32 v20, v20, v21
	v_fmamk_f32 v20, v20, 0x3c000000, v179
	v_rsq_f32_e32 v20, v20
	s_nop 0
	v_mul_f32_e32 v16, v156, v20
	v_pk_mul_f32 v[8:9], v[8:9], v[16:17] op_sel_hi:[1,0]
	v_pk_mul_f32 v[10:11], v[10:11], v[16:17] op_sel_hi:[1,0]
	v_pk_mul_f32 v[12:13], v[12:13], v[16:17] op_sel_hi:[1,0]
	v_pk_mul_f32 v[14:15], v[14:15], v[16:17] op_sel_hi:[1,0]
	v_pk_mul_f32 v[10:11], v[134:135], v[10:11]
	v_pk_mul_f32 v[8:9], v[132:133], v[8:9]
	v_pk_mul_f32 v[14:15], v[130:131], v[14:15]
	v_pk_mul_f32 v[12:13], v[128:129], v[12:13]
	v_cvt_pk_bf16_f32 v8, v8, v9
	v_cvt_pk_bf16_f32 v9, v10, v11
	v_add_u32_e32 v16, s4, v168
	v_cvt_pk_bf16_f32 v10, v12, v13
	v_cvt_pk_bf16_f32 v11, v14, v15
	ds_read_b128 v[12:15], v187 offset:16
	v_ashrrev_i32_e32 v17, 31, v16
	s_waitcnt lgkmcnt(0)
	v_mov_b32_e32 v18, v13
	v_mov_b32_e32 v19, v14
	v_mov_b32_e32 v13, v15
	v_pk_add_f32 v[12:13], v[18:19], v[12:13]
	s_nop 0
	v_add_f32_e32 v12, v12, v13
	v_fmamk_f32 v12, v12, 0x3c000000, v179
	v_rsq_f32_e32 v14, v12
	v_lshlrev_b64 v[12:13], 12, v[16:17]
	v_lshl_add_u64 v[154:155], v[120:121], 0, v[12:13]
	global_store_dwordx4 v[154:155], v[8:11], off nt
	s_nop 1
	v_mul_f32_e32 v8, v156, v14
	v_pk_mul_f32 v[0:1], v[0:1], v[8:9] op_sel_hi:[1,0]
	v_pk_mul_f32 v[2:3], v[2:3], v[8:9] op_sel_hi:[1,0]
	v_pk_mul_f32 v[4:5], v[4:5], v[8:9] op_sel_hi:[1,0]
	v_pk_mul_f32 v[6:7], v[6:7], v[8:9] op_sel_hi:[1,0]
	v_pk_mul_f32 v[2:3], v[134:135], v[2:3]
	v_pk_mul_f32 v[0:1], v[132:133], v[0:1]
	v_pk_mul_f32 v[6:7], v[130:131], v[6:7]
	v_pk_mul_f32 v[4:5], v[128:129], v[4:5]
	v_cvt_pk_bf16_f32 v128, v0, v1
	v_cvt_pk_bf16_f32 v129, v2, v3
	s_nop 0
	v_cvt_pk_bf16_f32 v130, v4, v5
	v_cvt_pk_bf16_f32 v131, v6, v7
	s_andn2_b64 vcc, exec, s[2:3]
	s_mov_b64 s[2:3], -1
	global_store_dwordx4 v[154:155], v[128:131], off offset:256 nt
	s_cbranch_vccnz .LBB0_1014
